# dead-code elimination strategy: the per-step lane-address computation (mbcnt, shift, xor) left dead by the DPP butterfly conversion is deleted at 77 attention sites
# baseline (speedup 1.0000x reference)
; __device__ __forceinline__ float shfl_idx_f(float v, int src) { return __int_as_float(__builtin_amdgcn_ds_bpermute(src << 2, __float_as_int(v))); }
; __device__ __forceinline__ void ssd_sample_item(const Params& p, int item, const int wv) {
;     ...
;   const float dt = DT[(size_t)tok * 16 + h];
;   const float dA = __expf(-dt * __expf(p.in[16][h]));
;   const float* st = p.in[6] + ((size_t)(b * 16 + h) * 64) * 128;
;   float* so = p.out + O_SSMS + ((size_t)(b * 16 + h) * 64) * 128;
;   float ymine = 0.f;
; #pragma unroll 8
;   for (int r = 0; r < 32; ++r) {
;     const int pp = 2 * r + hf;
;     f32x4 hv = *(const f32x4*)(st + (size_t)pp * 128 + n4);
;     const float xp = shfl_idx_f(x, pp) * dt;
;     f32x4 hn;
;     float yp = 0.f;
; #pragma unroll
;     for (int e = 0; e < 4; ++e) { hn[e] = dA * hv[e] + xp * Bv[e]; yp += hn[e] * Cv[e]; }
;     *(f32x4*)(so + (size_t)pp * 128 + n4) = hn;
.LBB0_457:
	v_subrev_u32_e32 v65, 56, v32
	v_mbcnt_lo_u32_b32 v3, -1, 0
	v_mbcnt_hi_u32_b32 v3, -1, v3
	v_lshlrev_b32_e32 v3, 2, v3
	v_xor_b32_e32 v22, 64, v3
	v_xor_b32_e32 v23, 32, v3
	v_xor_b32_e32 v24, 16, v3
	v_xor_b32_e32 v25, 8, v3
	v_xor_b32_e32 v26, 4, v3
	s_mov_b64 s[12:13], 0x0
	v_lshl_add_u64 v[66:67], v[18:19], 0, s[12:13]
	global_load_dwordx4 v[84:87], v[66:67], off
	global_load_dwordx4 v[88:91], v[66:67], off offset:1024
	global_load_dwordx4 v[92:95], v[66:67], off offset:2048
	global_load_dwordx4 v[96:99], v[66:67], off offset:3072
	s_mov_b64 s[12:13], 0x1000
	v_lshl_add_u64 v[66:67], v[18:19], 0, s[12:13]
	global_load_dwordx4 v[100:103], v[66:67], off
	global_load_dwordx4 v[104:107], v[66:67], off offset:1024
	global_load_dwordx4 v[108:111], v[66:67], off offset:2048
	global_load_dwordx4 v[112:115], v[66:67], off offset:3072
	s_mov_b64 s[12:13], 0x2000
	v_lshl_add_u64 v[66:67], v[18:19], 0, s[12:13]
	global_load_dwordx4 v[116:119], v[66:67], off
	global_load_dwordx4 v[120:123], v[66:67], off offset:1024
	global_load_dwordx4 v[124:127], v[66:67], off offset:2048
	global_load_dwordx4 v[128:131], v[66:67], off offset:3072
	s_mov_b64 s[12:13], 0x3000
	v_lshl_add_u64 v[66:67], v[18:19], 0, s[12:13]
	global_load_dwordx4 v[132:135], v[66:67], off
	global_load_dwordx4 v[136:139], v[66:67], off offset:1024
	global_load_dwordx4 v[140:143], v[66:67], off offset:2048
	global_load_dwordx4 v[144:147], v[66:67], off offset:3072
	s_mov_b64 s[12:13], 0x4000
	v_lshl_add_u64 v[66:67], v[18:19], 0, s[12:13]
	global_load_dwordx4 v[148:151], v[66:67], off
	global_load_dwordx4 v[152:155], v[66:67], off offset:1024
	global_load_dwordx4 v[156:159], v[66:67], off offset:2048
	global_load_dwordx4 v[164:167], v[66:67], off offset:3072
	s_mov_b64 s[12:13], 0x5000
	v_lshl_add_u64 v[66:67], v[18:19], 0, s[12:13]
	global_load_dwordx4 v[168:171], v[66:67], off
	global_load_dwordx4 v[172:175], v[66:67], off offset:1024
	global_load_dwordx4 v[176:179], v[66:67], off offset:2048
	global_load_dwordx4 v[180:183], v[66:67], off offset:3072
	s_mov_b64 s[12:13], 0x6000
	v_lshl_add_u64 v[66:67], v[18:19], 0, s[12:13]
	global_load_dwordx4 v[184:187], v[66:67], off
	global_load_dwordx4 v[188:191], v[66:67], off offset:1024
	global_load_dwordx4 v[192:195], v[66:67], off offset:2048
	global_load_dwordx4 v[196:199], v[66:67], off offset:3072
	s_mov_b64 s[12:13], 0x7000
	v_lshl_add_u64 v[66:67], v[18:19], 0, s[12:13]
	global_load_dwordx4 v[200:203], v[66:67], off
	global_load_dwordx4 v[204:207], v[66:67], off offset:1024
	global_load_dwordx4 v[208:211], v[66:67], off offset:2048
	global_load_dwordx4 v[212:215], v[66:67], off offset:3072
	ds_bpermute_b32 v33, v65, v31
	ds_bpermute_b32 v34, v65, v31 offset:8
	ds_bpermute_b32 v35, v65, v31 offset:16
	ds_bpermute_b32 v36, v65, v31 offset:24
	ds_bpermute_b32 v37, v65, v31 offset:32
	ds_bpermute_b32 v38, v65, v31 offset:40
	ds_bpermute_b32 v39, v65, v31 offset:48
	ds_bpermute_b32 v40, v65, v31 offset:56
	ds_bpermute_b32 v41, v65, v31 offset:64
	ds_bpermute_b32 v42, v65, v31 offset:72
	ds_bpermute_b32 v43, v65, v31 offset:80
	ds_bpermute_b32 v44, v65, v31 offset:88
	ds_bpermute_b32 v45, v65, v31 offset:96
	ds_bpermute_b32 v46, v65, v31 offset:104
	ds_bpermute_b32 v47, v65, v31 offset:112
	ds_bpermute_b32 v48, v65, v31 offset:120
	s_waitcnt lgkmcnt(0)
	ds_bpermute_b32 v49, v65, v31 offset:128
	ds_bpermute_b32 v50, v65, v31 offset:136
	ds_bpermute_b32 v51, v65, v31 offset:144
	ds_bpermute_b32 v52, v65, v31 offset:152
	ds_bpermute_b32 v53, v65, v31 offset:160
	ds_bpermute_b32 v54, v65, v31 offset:168
	ds_bpermute_b32 v55, v65, v31 offset:176
	ds_bpermute_b32 v56, v65, v31 offset:184
	ds_bpermute_b32 v57, v65, v31 offset:192
	ds_bpermute_b32 v58, v65, v31 offset:200
	ds_bpermute_b32 v59, v65, v31 offset:208
	ds_bpermute_b32 v60, v65, v31 offset:216
	ds_bpermute_b32 v61, v65, v31 offset:224
	ds_bpermute_b32 v62, v65, v31 offset:232
	ds_bpermute_b32 v63, v65, v31 offset:240
	ds_bpermute_b32 v64, v65, v31 offset:248
	s_waitcnt lgkmcnt(0)
	v_mul_f32_e32 v33, v30, v33
	v_mul_f32_e32 v34, v30, v34
	v_mul_f32_e32 v35, v30, v35
	v_mul_f32_e32 v36, v30, v36
	v_mul_f32_e32 v37, v30, v37
	v_mul_f32_e32 v38, v30, v38
	v_mul_f32_e32 v39, v30, v39
	v_mul_f32_e32 v40, v30, v40
	v_mul_f32_e32 v41, v30, v41
	v_mul_f32_e32 v42, v30, v42
	v_mul_f32_e32 v43, v30, v43
	v_mul_f32_e32 v44, v30, v44
	v_mul_f32_e32 v45, v30, v45
	v_mul_f32_e32 v46, v30, v46
	v_mul_f32_e32 v47, v30, v47
	v_mul_f32_e32 v48, v30, v48
	v_mul_f32_e32 v49, v30, v49
	v_mul_f32_e32 v50, v30, v50
	v_mul_f32_e32 v51, v30, v51
	v_mul_f32_e32 v52, v30, v52
	v_mul_f32_e32 v53, v30, v53
	v_mul_f32_e32 v54, v30, v54
	v_mul_f32_e32 v55, v30, v55
	v_mul_f32_e32 v56, v30, v56
	v_mul_f32_e32 v57, v30, v57
	v_mul_f32_e32 v58, v30, v58
	v_mul_f32_e32 v59, v30, v59
	v_mul_f32_e32 v60, v30, v60
	v_mul_f32_e32 v61, v30, v61
	v_mul_f32_e32 v62, v30, v62
	v_mul_f32_e32 v63, v30, v63
	v_mul_f32_e32 v64, v30, v64
	s_mov_b64 s[12:13], 0x4ee4000
	v_lshl_add_u64 v[68:69], v[20:21], 0, s[12:13]
	s_waitcnt vmcnt(31)
	v_mul_f32_e32 v216, v6, v33
	v_mul_f32_e32 v217, v7, v33
	v_mul_f32_e32 v218, v10, v33
	v_mul_f32_e32 v219, v11, v33
	v_fma_f32 v84, v12, v84, v216
	v_fma_f32 v85, v12, v85, v217
	v_fma_f32 v86, v12, v86, v218
	v_fma_f32 v87, v12, v87, v219
	global_store_dwordx4 v[68:69], v[84:87], off
	v_mul_f32_e32 v216, v8, v84
	v_mul_f32_e32 v217, v9, v85
	v_mul_f32_e32 v218, v14, v86
	v_mul_f32_e32 v219, v15, v87
	v_add_f32_e32 v33, 0, v216
	v_add_f32_e32 v33, v217, v33
	v_add_f32_e32 v33, v218, v33
	v_add_f32_e32 v33, v219, v33
	s_waitcnt vmcnt(31)
; __device__ __forceinline__ float shfl_idx_f(float v, int src) { return __int_as_float(__builtin_amdgcn_ds_bpermute(src << 2, __float_as_int(v))); }
; __device__ __forceinline__ void ssd_sample_item(const Params& p, int item, const int wv) {
;     ...
;   for (int r = 0; r < 32; ++r) {
;     const int pp = 2 * r + hf;
;     f32x4 hv = *(const f32x4*)(st + (size_t)pp * 128 + n4);
;     const float xp = shfl_idx_f(x, pp) * dt;
;     f32x4 hn;
;     float yp = 0.f;
; #pragma unroll
;     for (int e = 0; e < 4; ++e) { hn[e] = dA * hv[e] + xp * Bv[e]; yp += hn[e] * Cv[e]; }
;     *(f32x4*)(so + (size_t)pp * 128 + n4) = hn;
	v_mul_f32_e32 v216, v6, v34
	v_mul_f32_e32 v217, v7, v34
	v_mul_f32_e32 v218, v10, v34
	v_mul_f32_e32 v219, v11, v34
	v_fma_f32 v88, v12, v88, v216
	v_fma_f32 v89, v12, v89, v217
	v_fma_f32 v90, v12, v90, v218
	v_fma_f32 v91, v12, v91, v219
	global_store_dwordx4 v[68:69], v[88:91], off offset:1024
	v_mul_f32_e32 v216, v8, v88
	v_mul_f32_e32 v217, v9, v89
	v_mul_f32_e32 v218, v14, v90
	v_mul_f32_e32 v219, v15, v91
	v_add_f32_e32 v34, 0, v216
	v_add_f32_e32 v34, v217, v34
	v_add_f32_e32 v34, v218, v34
	v_add_f32_e32 v34, v219, v34
	s_waitcnt vmcnt(31)
	v_mul_f32_e32 v216, v6, v35
	v_mul_f32_e32 v217, v7, v35
	v_mul_f32_e32 v218, v10, v35
	v_mul_f32_e32 v219, v11, v35
	v_fma_f32 v92, v12, v92, v216
	v_fma_f32 v93, v12, v93, v217
	v_fma_f32 v94, v12, v94, v218
	v_fma_f32 v95, v12, v95, v219
	global_store_dwordx4 v[68:69], v[92:95], off offset:2048
	v_mul_f32_e32 v216, v8, v92
	v_mul_f32_e32 v217, v9, v93
	v_mul_f32_e32 v218, v14, v94
	v_mul_f32_e32 v219, v15, v95
	v_add_f32_e32 v35, 0, v216
	v_add_f32_e32 v35, v217, v35
	v_add_f32_e32 v35, v218, v35
	v_add_f32_e32 v35, v219, v35
	s_waitcnt vmcnt(31)
	v_mul_f32_e32 v216, v6, v36
	v_mul_f32_e32 v217, v7, v36
	v_mul_f32_e32 v218, v10, v36
	v_mul_f32_e32 v219, v11, v36
	v_fma_f32 v96, v12, v96, v216
	v_fma_f32 v97, v12, v97, v217
	v_fma_f32 v98, v12, v98, v218
	v_fma_f32 v99, v12, v99, v219
	global_store_dwordx4 v[68:69], v[96:99], off offset:3072
	v_mul_f32_e32 v216, v8, v96
	v_mul_f32_e32 v217, v9, v97
	v_mul_f32_e32 v218, v14, v98
	v_mul_f32_e32 v219, v15, v99
	v_add_f32_e32 v36, 0, v216
	v_add_f32_e32 v36, v217, v36
	v_add_f32_e32 v36, v218, v36
	v_add_f32_e32 v36, v219, v36
	s_mov_b64 s[12:13], 0x4ee5000
	v_lshl_add_u64 v[68:69], v[20:21], 0, s[12:13]
	s_waitcnt vmcnt(31)
	v_mul_f32_e32 v216, v6, v37
	v_mul_f32_e32 v217, v7, v37
	v_mul_f32_e32 v218, v10, v37
	v_mul_f32_e32 v219, v11, v37
	v_fma_f32 v100, v12, v100, v216
	v_fma_f32 v101, v12, v101, v217
	v_fma_f32 v102, v12, v102, v218
	v_fma_f32 v103, v12, v103, v219
	global_store_dwordx4 v[68:69], v[100:103], off
	v_mul_f32_e32 v216, v8, v100
	v_mul_f32_e32 v217, v9, v101
	v_mul_f32_e32 v218, v14, v102
	v_mul_f32_e32 v219, v15, v103
	v_add_f32_e32 v37, 0, v216
	v_add_f32_e32 v37, v217, v37
	v_add_f32_e32 v37, v218, v37
	v_add_f32_e32 v37, v219, v37
	s_waitcnt vmcnt(31)
	v_mul_f32_e32 v216, v6, v38
	v_mul_f32_e32 v217, v7, v38
	v_mul_f32_e32 v218, v10, v38
	v_mul_f32_e32 v219, v11, v38
	v_fma_f32 v104, v12, v104, v216
	v_fma_f32 v105, v12, v105, v217
	v_fma_f32 v106, v12, v106, v218
	v_fma_f32 v107, v12, v107, v219
	global_store_dwordx4 v[68:69], v[104:107], off offset:1024
	v_mul_f32_e32 v216, v8, v104
	v_mul_f32_e32 v217, v9, v105
	v_mul_f32_e32 v218, v14, v106
	v_mul_f32_e32 v219, v15, v107
	v_add_f32_e32 v38, 0, v216
	v_add_f32_e32 v38, v217, v38
	v_add_f32_e32 v38, v218, v38
	v_add_f32_e32 v38, v219, v38
	s_waitcnt vmcnt(31)
	v_mul_f32_e32 v216, v6, v39
	v_mul_f32_e32 v217, v7, v39
	v_mul_f32_e32 v218, v10, v39
	v_mul_f32_e32 v219, v11, v39
	v_fma_f32 v108, v12, v108, v216
	v_fma_f32 v109, v12, v109, v217
	v_fma_f32 v110, v12, v110, v218
	v_fma_f32 v111, v12, v111, v219
	global_store_dwordx4 v[68:69], v[108:111], off offset:2048
	v_mul_f32_e32 v216, v8, v108
	v_mul_f32_e32 v217, v9, v109
	v_mul_f32_e32 v218, v14, v110
	v_mul_f32_e32 v219, v15, v111
	v_add_f32_e32 v39, 0, v216
	v_add_f32_e32 v39, v217, v39
	v_add_f32_e32 v39, v218, v39
	v_add_f32_e32 v39, v219, v39
	s_waitcnt vmcnt(31)
	v_mul_f32_e32 v216, v6, v40
	v_mul_f32_e32 v217, v7, v40
	v_mul_f32_e32 v218, v10, v40
	v_mul_f32_e32 v219, v11, v40
	v_fma_f32 v112, v12, v112, v216
	v_fma_f32 v113, v12, v113, v217
	v_fma_f32 v114, v12, v114, v218
	v_fma_f32 v115, v12, v115, v219
	global_store_dwordx4 v[68:69], v[112:115], off offset:3072
	v_mul_f32_e32 v216, v8, v112
	v_mul_f32_e32 v217, v9, v113
	v_mul_f32_e32 v218, v14, v114
	v_mul_f32_e32 v219, v15, v115
	v_add_f32_e32 v40, 0, v216
	v_add_f32_e32 v40, v217, v40
	v_add_f32_e32 v40, v218, v40
	v_add_f32_e32 v40, v219, v40
	s_mov_b64 s[12:13], 0x4ee6000
	v_lshl_add_u64 v[68:69], v[20:21], 0, s[12:13]
	s_waitcnt vmcnt(31)
	v_mul_f32_e32 v216, v6, v41
	v_mul_f32_e32 v217, v7, v41
	v_mul_f32_e32 v218, v10, v41
	v_mul_f32_e32 v219, v11, v41
	v_fma_f32 v116, v12, v116, v216
	v_fma_f32 v117, v12, v117, v217
	v_fma_f32 v118, v12, v118, v218
	v_fma_f32 v119, v12, v119, v219
	global_store_dwordx4 v[68:69], v[116:119], off
	v_mul_f32_e32 v216, v8, v116
	v_mul_f32_e32 v217, v9, v117
	v_mul_f32_e32 v218, v14, v118
	v_mul_f32_e32 v219, v15, v119
	v_add_f32_e32 v41, 0, v216
	v_add_f32_e32 v41, v217, v41
	v_add_f32_e32 v41, v218, v41
	v_add_f32_e32 v41, v219, v41
	s_waitcnt vmcnt(31)
	v_mul_f32_e32 v216, v6, v42
	v_mul_f32_e32 v217, v7, v42
	v_mul_f32_e32 v218, v10, v42
	v_mul_f32_e32 v219, v11, v42
	v_fma_f32 v120, v12, v120, v216
	v_fma_f32 v121, v12, v121, v217
	v_fma_f32 v122, v12, v122, v218
	v_fma_f32 v123, v12, v123, v219
	global_store_dwordx4 v[68:69], v[120:123], off offset:1024
	v_mul_f32_e32 v216, v8, v120
	v_mul_f32_e32 v217, v9, v121
	v_mul_f32_e32 v218, v14, v122
	v_mul_f32_e32 v219, v15, v123
	v_add_f32_e32 v42, 0, v216
	v_add_f32_e32 v42, v217, v42
	v_add_f32_e32 v42, v218, v42
	v_add_f32_e32 v42, v219, v42
	s_waitcnt vmcnt(31)
	v_mul_f32_e32 v216, v6, v43
	v_mul_f32_e32 v217, v7, v43
	v_mul_f32_e32 v218, v10, v43
	v_mul_f32_e32 v219, v11, v43
	v_fma_f32 v124, v12, v124, v216
	v_fma_f32 v125, v12, v125, v217
	v_fma_f32 v126, v12, v126, v218
	v_fma_f32 v127, v12, v127, v219
	global_store_dwordx4 v[68:69], v[124:127], off offset:2048
	v_mul_f32_e32 v216, v8, v124
	v_mul_f32_e32 v217, v9, v125
	v_mul_f32_e32 v218, v14, v126
	v_mul_f32_e32 v219, v15, v127
	v_add_f32_e32 v43, 0, v216
	v_add_f32_e32 v43, v217, v43
	v_add_f32_e32 v43, v218, v43
	v_add_f32_e32 v43, v219, v43
	s_waitcnt vmcnt(31)
; __device__ __forceinline__ float shfl_idx_f(float v, int src) { return __int_as_float(__builtin_amdgcn_ds_bpermute(src << 2, __float_as_int(v))); }
; __device__ __forceinline__ void ssd_sample_item(const Params& p, int item, const int wv) {
;     ...
;   for (int r = 0; r < 32; ++r) {
;     const int pp = 2 * r + hf;
;     f32x4 hv = *(const f32x4*)(st + (size_t)pp * 128 + n4);
;     const float xp = shfl_idx_f(x, pp) * dt;
;     f32x4 hn;
;     float yp = 0.f;
; #pragma unroll
;     for (int e = 0; e < 4; ++e) { hn[e] = dA * hv[e] + xp * Bv[e]; yp += hn[e] * Cv[e]; }
;     *(f32x4*)(so + (size_t)pp * 128 + n4) = hn;
	v_mul_f32_e32 v216, v6, v44
	v_mul_f32_e32 v217, v7, v44
	v_mul_f32_e32 v218, v10, v44
	v_mul_f32_e32 v219, v11, v44
	v_fma_f32 v128, v12, v128, v216
	v_fma_f32 v129, v12, v129, v217
	v_fma_f32 v130, v12, v130, v218
	v_fma_f32 v131, v12, v131, v219
	global_store_dwordx4 v[68:69], v[128:131], off offset:3072
	v_mul_f32_e32 v216, v8, v128
	v_mul_f32_e32 v217, v9, v129
	v_mul_f32_e32 v218, v14, v130
	v_mul_f32_e32 v219, v15, v131
	v_add_f32_e32 v44, 0, v216
	v_add_f32_e32 v44, v217, v44
	v_add_f32_e32 v44, v218, v44
	v_add_f32_e32 v44, v219, v44
	s_mov_b64 s[12:13], 0x4ee7000
	v_lshl_add_u64 v[68:69], v[20:21], 0, s[12:13]
	s_waitcnt vmcnt(31)
	v_mul_f32_e32 v216, v6, v45
	v_mul_f32_e32 v217, v7, v45
	v_mul_f32_e32 v218, v10, v45
	v_mul_f32_e32 v219, v11, v45
	v_fma_f32 v132, v12, v132, v216
	v_fma_f32 v133, v12, v133, v217
	v_fma_f32 v134, v12, v134, v218
	v_fma_f32 v135, v12, v135, v219
	global_store_dwordx4 v[68:69], v[132:135], off
	v_mul_f32_e32 v216, v8, v132
	v_mul_f32_e32 v217, v9, v133
	v_mul_f32_e32 v218, v14, v134
	v_mul_f32_e32 v219, v15, v135
	v_add_f32_e32 v45, 0, v216
	v_add_f32_e32 v45, v217, v45
	v_add_f32_e32 v45, v218, v45
	v_add_f32_e32 v45, v219, v45
	s_waitcnt vmcnt(31)
	v_mul_f32_e32 v216, v6, v46
	v_mul_f32_e32 v217, v7, v46
	v_mul_f32_e32 v218, v10, v46
	v_mul_f32_e32 v219, v11, v46
	v_fma_f32 v136, v12, v136, v216
	v_fma_f32 v137, v12, v137, v217
	v_fma_f32 v138, v12, v138, v218
	v_fma_f32 v139, v12, v139, v219
	global_store_dwordx4 v[68:69], v[136:139], off offset:1024
	v_mul_f32_e32 v216, v8, v136
	v_mul_f32_e32 v217, v9, v137
	v_mul_f32_e32 v218, v14, v138
	v_mul_f32_e32 v219, v15, v139
	v_add_f32_e32 v46, 0, v216
	v_add_f32_e32 v46, v217, v46
	v_add_f32_e32 v46, v218, v46
	v_add_f32_e32 v46, v219, v46
	s_waitcnt vmcnt(31)
	v_mul_f32_e32 v216, v6, v47
	v_mul_f32_e32 v217, v7, v47
	v_mul_f32_e32 v218, v10, v47
	v_mul_f32_e32 v219, v11, v47
	v_fma_f32 v140, v12, v140, v216
	v_fma_f32 v141, v12, v141, v217
	v_fma_f32 v142, v12, v142, v218
	v_fma_f32 v143, v12, v143, v219
	global_store_dwordx4 v[68:69], v[140:143], off offset:2048
	v_mul_f32_e32 v216, v8, v140
	v_mul_f32_e32 v217, v9, v141
	v_mul_f32_e32 v218, v14, v142
	v_mul_f32_e32 v219, v15, v143
	v_add_f32_e32 v47, 0, v216
	v_add_f32_e32 v47, v217, v47
	v_add_f32_e32 v47, v218, v47
	v_add_f32_e32 v47, v219, v47
	s_waitcnt vmcnt(31)
	v_mul_f32_e32 v216, v6, v48
	v_mul_f32_e32 v217, v7, v48
	v_mul_f32_e32 v218, v10, v48
	v_mul_f32_e32 v219, v11, v48
	v_fma_f32 v144, v12, v144, v216
	v_fma_f32 v145, v12, v145, v217
	v_fma_f32 v146, v12, v146, v218
	v_fma_f32 v147, v12, v147, v219
	global_store_dwordx4 v[68:69], v[144:147], off offset:3072
	v_mul_f32_e32 v216, v8, v144
	v_mul_f32_e32 v217, v9, v145
	v_mul_f32_e32 v218, v14, v146
	v_mul_f32_e32 v219, v15, v147
	v_add_f32_e32 v48, 0, v216
	v_add_f32_e32 v48, v217, v48
	v_add_f32_e32 v48, v218, v48
	v_add_f32_e32 v48, v219, v48
	s_mov_b64 s[12:13], 0x4ee8000
	v_lshl_add_u64 v[68:69], v[20:21], 0, s[12:13]
	s_waitcnt vmcnt(31)
	v_mul_f32_e32 v216, v6, v49
	v_mul_f32_e32 v217, v7, v49
	v_mul_f32_e32 v218, v10, v49
	v_mul_f32_e32 v219, v11, v49
	v_fma_f32 v148, v12, v148, v216
	v_fma_f32 v149, v12, v149, v217
	v_fma_f32 v150, v12, v150, v218
	v_fma_f32 v151, v12, v151, v219
	global_store_dwordx4 v[68:69], v[148:151], off
	v_mul_f32_e32 v216, v8, v148
	v_mul_f32_e32 v217, v9, v149
	v_mul_f32_e32 v218, v14, v150
	v_mul_f32_e32 v219, v15, v151
	v_add_f32_e32 v49, 0, v216
	v_add_f32_e32 v49, v217, v49
	v_add_f32_e32 v49, v218, v49
	v_add_f32_e32 v49, v219, v49
	s_waitcnt vmcnt(31)
	v_mul_f32_e32 v216, v6, v50
	v_mul_f32_e32 v217, v7, v50
	v_mul_f32_e32 v218, v10, v50
	v_mul_f32_e32 v219, v11, v50
	v_fma_f32 v152, v12, v152, v216
	v_fma_f32 v153, v12, v153, v217
	v_fma_f32 v154, v12, v154, v218
	v_fma_f32 v155, v12, v155, v219
	global_store_dwordx4 v[68:69], v[152:155], off offset:1024
	v_mul_f32_e32 v216, v8, v152
	v_mul_f32_e32 v217, v9, v153
	v_mul_f32_e32 v218, v14, v154
	v_mul_f32_e32 v219, v15, v155
	v_add_f32_e32 v50, 0, v216
	v_add_f32_e32 v50, v217, v50
	v_add_f32_e32 v50, v218, v50
	v_add_f32_e32 v50, v219, v50
	s_waitcnt vmcnt(31)
	v_mul_f32_e32 v216, v6, v51
	v_mul_f32_e32 v217, v7, v51
	v_mul_f32_e32 v218, v10, v51
	v_mul_f32_e32 v219, v11, v51
	v_fma_f32 v156, v12, v156, v216
	v_fma_f32 v157, v12, v157, v217
	v_fma_f32 v158, v12, v158, v218
	v_fma_f32 v159, v12, v159, v219
	global_store_dwordx4 v[68:69], v[156:159], off offset:2048
	v_mul_f32_e32 v216, v8, v156
	v_mul_f32_e32 v217, v9, v157
	v_mul_f32_e32 v218, v14, v158
	v_mul_f32_e32 v219, v15, v159
	v_add_f32_e32 v51, 0, v216
	v_add_f32_e32 v51, v217, v51
	v_add_f32_e32 v51, v218, v51
	v_add_f32_e32 v51, v219, v51
	s_waitcnt vmcnt(31)
	v_mul_f32_e32 v216, v6, v52
	v_mul_f32_e32 v217, v7, v52
	v_mul_f32_e32 v218, v10, v52
	v_mul_f32_e32 v219, v11, v52
	v_fma_f32 v164, v12, v164, v216
	v_fma_f32 v165, v12, v165, v217
	v_fma_f32 v166, v12, v166, v218
	v_fma_f32 v167, v12, v167, v219
	global_store_dwordx4 v[68:69], v[164:167], off offset:3072
	v_mul_f32_e32 v216, v8, v164
	v_mul_f32_e32 v217, v9, v165
	v_mul_f32_e32 v218, v14, v166
	v_mul_f32_e32 v219, v15, v167
	v_add_f32_e32 v52, 0, v216
	v_add_f32_e32 v52, v217, v52
	v_add_f32_e32 v52, v218, v52
	v_add_f32_e32 v52, v219, v52
	s_mov_b64 s[12:13], 0x4ee9000
	v_lshl_add_u64 v[68:69], v[20:21], 0, s[12:13]
	s_waitcnt vmcnt(31)
	v_mul_f32_e32 v216, v6, v53
	v_mul_f32_e32 v217, v7, v53
	v_mul_f32_e32 v218, v10, v53
	v_mul_f32_e32 v219, v11, v53
	v_fma_f32 v168, v12, v168, v216
	v_fma_f32 v169, v12, v169, v217
	v_fma_f32 v170, v12, v170, v218
	v_fma_f32 v171, v12, v171, v219
	global_store_dwordx4 v[68:69], v[168:171], off
	v_mul_f32_e32 v216, v8, v168
	v_mul_f32_e32 v217, v9, v169
	v_mul_f32_e32 v218, v14, v170
	v_mul_f32_e32 v219, v15, v171
	v_add_f32_e32 v53, 0, v216
	v_add_f32_e32 v53, v217, v53
	v_add_f32_e32 v53, v218, v53
	v_add_f32_e32 v53, v219, v53
	s_waitcnt vmcnt(31)
; __device__ __forceinline__ float shfl_idx_f(float v, int src) { return __int_as_float(__builtin_amdgcn_ds_bpermute(src << 2, __float_as_int(v))); }
; __device__ __forceinline__ void ssd_sample_item(const Params& p, int item, const int wv) {
;     ...
;   for (int r = 0; r < 32; ++r) {
;     const int pp = 2 * r + hf;
;     f32x4 hv = *(const f32x4*)(st + (size_t)pp * 128 + n4);
;     const float xp = shfl_idx_f(x, pp) * dt;
;     f32x4 hn;
;     float yp = 0.f;
; #pragma unroll
;     for (int e = 0; e < 4; ++e) { hn[e] = dA * hv[e] + xp * Bv[e]; yp += hn[e] * Cv[e]; }
;     *(f32x4*)(so + (size_t)pp * 128 + n4) = hn;
	v_mul_f32_e32 v216, v6, v54
	v_mul_f32_e32 v217, v7, v54
	v_mul_f32_e32 v218, v10, v54
	v_mul_f32_e32 v219, v11, v54
	v_fma_f32 v172, v12, v172, v216
	v_fma_f32 v173, v12, v173, v217
	v_fma_f32 v174, v12, v174, v218
	v_fma_f32 v175, v12, v175, v219
	global_store_dwordx4 v[68:69], v[172:175], off offset:1024
	v_mul_f32_e32 v216, v8, v172
	v_mul_f32_e32 v217, v9, v173
	v_mul_f32_e32 v218, v14, v174
	v_mul_f32_e32 v219, v15, v175
	v_add_f32_e32 v54, 0, v216
	v_add_f32_e32 v54, v217, v54
	v_add_f32_e32 v54, v218, v54
	v_add_f32_e32 v54, v219, v54
	s_waitcnt vmcnt(31)
	v_mul_f32_e32 v216, v6, v55
	v_mul_f32_e32 v217, v7, v55
	v_mul_f32_e32 v218, v10, v55
	v_mul_f32_e32 v219, v11, v55
	v_fma_f32 v176, v12, v176, v216
	v_fma_f32 v177, v12, v177, v217
	v_fma_f32 v178, v12, v178, v218
	v_fma_f32 v179, v12, v179, v219
	global_store_dwordx4 v[68:69], v[176:179], off offset:2048
	v_mul_f32_e32 v216, v8, v176
	v_mul_f32_e32 v217, v9, v177
	v_mul_f32_e32 v218, v14, v178
	v_mul_f32_e32 v219, v15, v179
	v_add_f32_e32 v55, 0, v216
	v_add_f32_e32 v55, v217, v55
	v_add_f32_e32 v55, v218, v55
	v_add_f32_e32 v55, v219, v55
	s_waitcnt vmcnt(31)
	v_mul_f32_e32 v216, v6, v56
	v_mul_f32_e32 v217, v7, v56
	v_mul_f32_e32 v218, v10, v56
	v_mul_f32_e32 v219, v11, v56
	v_fma_f32 v180, v12, v180, v216
	v_fma_f32 v181, v12, v181, v217
	v_fma_f32 v182, v12, v182, v218
	v_fma_f32 v183, v12, v183, v219
	global_store_dwordx4 v[68:69], v[180:183], off offset:3072
	v_mul_f32_e32 v216, v8, v180
	v_mul_f32_e32 v217, v9, v181
	v_mul_f32_e32 v218, v14, v182
	v_mul_f32_e32 v219, v15, v183
	v_add_f32_e32 v56, 0, v216
	v_add_f32_e32 v56, v217, v56
	v_add_f32_e32 v56, v218, v56
	v_add_f32_e32 v56, v219, v56
	s_mov_b64 s[12:13], 0x4eea000
	v_lshl_add_u64 v[68:69], v[20:21], 0, s[12:13]
	s_waitcnt vmcnt(31)
	v_mul_f32_e32 v216, v6, v57
	v_mul_f32_e32 v217, v7, v57
	v_mul_f32_e32 v218, v10, v57
	v_mul_f32_e32 v219, v11, v57
	v_fma_f32 v184, v12, v184, v216
	v_fma_f32 v185, v12, v185, v217
	v_fma_f32 v186, v12, v186, v218
	v_fma_f32 v187, v12, v187, v219
	global_store_dwordx4 v[68:69], v[184:187], off
	v_mul_f32_e32 v216, v8, v184
	v_mul_f32_e32 v217, v9, v185
	v_mul_f32_e32 v218, v14, v186
	v_mul_f32_e32 v219, v15, v187
	v_add_f32_e32 v57, 0, v216
	v_add_f32_e32 v57, v217, v57
	v_add_f32_e32 v57, v218, v57
	v_add_f32_e32 v57, v219, v57
	s_waitcnt vmcnt(31)
	v_mul_f32_e32 v216, v6, v58
	v_mul_f32_e32 v217, v7, v58
	v_mul_f32_e32 v218, v10, v58
	v_mul_f32_e32 v219, v11, v58
	v_fma_f32 v188, v12, v188, v216
	v_fma_f32 v189, v12, v189, v217
	v_fma_f32 v190, v12, v190, v218
	v_fma_f32 v191, v12, v191, v219
	global_store_dwordx4 v[68:69], v[188:191], off offset:1024
	v_mul_f32_e32 v216, v8, v188
	v_mul_f32_e32 v217, v9, v189
	v_mul_f32_e32 v218, v14, v190
	v_mul_f32_e32 v219, v15, v191
	v_add_f32_e32 v58, 0, v216
	v_add_f32_e32 v58, v217, v58
	v_add_f32_e32 v58, v218, v58
	v_add_f32_e32 v58, v219, v58
	s_waitcnt vmcnt(31)
	v_mul_f32_e32 v216, v6, v59
	v_mul_f32_e32 v217, v7, v59
	v_mul_f32_e32 v218, v10, v59
	v_mul_f32_e32 v219, v11, v59
	v_fma_f32 v192, v12, v192, v216
	v_fma_f32 v193, v12, v193, v217
	v_fma_f32 v194, v12, v194, v218
	v_fma_f32 v195, v12, v195, v219
	global_store_dwordx4 v[68:69], v[192:195], off offset:2048
	v_mul_f32_e32 v216, v8, v192
	v_mul_f32_e32 v217, v9, v193
	v_mul_f32_e32 v218, v14, v194
	v_mul_f32_e32 v219, v15, v195
	v_add_f32_e32 v59, 0, v216
	v_add_f32_e32 v59, v217, v59
	v_add_f32_e32 v59, v218, v59
	v_add_f32_e32 v59, v219, v59
	s_waitcnt vmcnt(31)
	v_mul_f32_e32 v216, v6, v60
	v_mul_f32_e32 v217, v7, v60
	v_mul_f32_e32 v218, v10, v60
	v_mul_f32_e32 v219, v11, v60
	v_fma_f32 v196, v12, v196, v216
	v_fma_f32 v197, v12, v197, v217
	v_fma_f32 v198, v12, v198, v218
	v_fma_f32 v199, v12, v199, v219
	global_store_dwordx4 v[68:69], v[196:199], off offset:3072
	v_mul_f32_e32 v216, v8, v196
	v_mul_f32_e32 v217, v9, v197
	v_mul_f32_e32 v218, v14, v198
	v_mul_f32_e32 v219, v15, v199
	v_add_f32_e32 v60, 0, v216
	v_add_f32_e32 v60, v217, v60
	v_add_f32_e32 v60, v218, v60
	v_add_f32_e32 v60, v219, v60
	s_mov_b64 s[12:13], 0x4eeb000
	v_lshl_add_u64 v[68:69], v[20:21], 0, s[12:13]
	s_waitcnt vmcnt(31)
	v_mul_f32_e32 v216, v6, v61
	v_mul_f32_e32 v217, v7, v61
	v_mul_f32_e32 v218, v10, v61
	v_mul_f32_e32 v219, v11, v61
	v_fma_f32 v200, v12, v200, v216
	v_fma_f32 v201, v12, v201, v217
	v_fma_f32 v202, v12, v202, v218
	v_fma_f32 v203, v12, v203, v219
	global_store_dwordx4 v[68:69], v[200:203], off
	v_mul_f32_e32 v216, v8, v200
	v_mul_f32_e32 v217, v9, v201
	v_mul_f32_e32 v218, v14, v202
	v_mul_f32_e32 v219, v15, v203
	v_add_f32_e32 v61, 0, v216
	v_add_f32_e32 v61, v217, v61
	v_add_f32_e32 v61, v218, v61
	v_add_f32_e32 v61, v219, v61
	s_waitcnt vmcnt(31)
	v_mul_f32_e32 v216, v6, v62
	v_mul_f32_e32 v217, v7, v62
	v_mul_f32_e32 v218, v10, v62
	v_mul_f32_e32 v219, v11, v62
	v_fma_f32 v204, v12, v204, v216
	v_fma_f32 v205, v12, v205, v217
	v_fma_f32 v206, v12, v206, v218
	v_fma_f32 v207, v12, v207, v219
	global_store_dwordx4 v[68:69], v[204:207], off offset:1024
	v_mul_f32_e32 v216, v8, v204
	v_mul_f32_e32 v217, v9, v205
	v_mul_f32_e32 v218, v14, v206
	v_mul_f32_e32 v219, v15, v207
	v_add_f32_e32 v62, 0, v216
	v_add_f32_e32 v62, v217, v62
	v_add_f32_e32 v62, v218, v62
	v_add_f32_e32 v62, v219, v62
	s_waitcnt vmcnt(31)
	v_mul_f32_e32 v216, v6, v63
	v_mul_f32_e32 v217, v7, v63
	v_mul_f32_e32 v218, v10, v63
	v_mul_f32_e32 v219, v11, v63
	v_fma_f32 v208, v12, v208, v216
	v_fma_f32 v209, v12, v209, v217
	v_fma_f32 v210, v12, v210, v218
	v_fma_f32 v211, v12, v211, v219
	global_store_dwordx4 v[68:69], v[208:211], off offset:2048
	v_mul_f32_e32 v216, v8, v208
	v_mul_f32_e32 v217, v9, v209
	v_mul_f32_e32 v218, v14, v210
	v_mul_f32_e32 v219, v15, v211
	v_add_f32_e32 v63, 0, v216
	v_add_f32_e32 v63, v217, v63
	v_add_f32_e32 v63, v218, v63
	v_add_f32_e32 v63, v219, v63
	s_waitcnt vmcnt(31)
; __device__ __forceinline__ float shfl_xor_f(float v, int mask) { const int l = lane_fresh(); return __int_as_float(__builtin_amdgcn_ds_bpermute((l ^ mask) << 2, __float_as_int(v))); }
; __device__ __forceinline__ void ssd_sample_item(const Params& p, int item, const int wv) {
;     ...
;     for (int e = 0; e < 4; ++e) { hn[e] = dA * hv[e] + xp * Bv[e]; yp += hn[e] * Cv[e]; }
;     *(f32x4*)(so + (size_t)pp * 128 + n4) = hn;
; #pragma unroll
;     for (int o = 16; o >= 1; o >>= 1) yp += shfl_xor_f(yp, o);
;     if ((lane & 31) == r) ymine = yp;
	v_mul_f32_e32 v216, v6, v64
	v_mul_f32_e32 v217, v7, v64
	v_mul_f32_e32 v218, v10, v64
	v_mul_f32_e32 v219, v11, v64
	v_fma_f32 v212, v12, v212, v216
	v_fma_f32 v213, v12, v213, v217
	v_fma_f32 v214, v12, v214, v218
	v_fma_f32 v215, v12, v215, v219
	global_store_dwordx4 v[68:69], v[212:215], off offset:3072
	v_mul_f32_e32 v216, v8, v212
	v_mul_f32_e32 v217, v9, v213
	v_mul_f32_e32 v218, v14, v214
	v_mul_f32_e32 v219, v15, v215
	v_add_f32_e32 v64, 0, v216
	v_add_f32_e32 v64, v217, v64
	v_add_f32_e32 v64, v218, v64
	v_add_f32_e32 v64, v219, v64
	ds_bpermute_b32 v66, v22, v33
	ds_bpermute_b32 v67, v22, v34
	ds_bpermute_b32 v68, v22, v35
	ds_bpermute_b32 v69, v22, v36
	ds_bpermute_b32 v70, v22, v37
	ds_bpermute_b32 v71, v22, v38
	ds_bpermute_b32 v72, v22, v39
	ds_bpermute_b32 v73, v22, v40
	ds_bpermute_b32 v74, v22, v41
	ds_bpermute_b32 v75, v22, v42
	ds_bpermute_b32 v76, v22, v43
	ds_bpermute_b32 v77, v22, v44
	ds_bpermute_b32 v78, v22, v45
	ds_bpermute_b32 v0, v22, v46
	ds_bpermute_b32 v1, v22, v47
	ds_bpermute_b32 v2, v22, v48
	s_waitcnt lgkmcnt(15)
	v_add_f32_e32 v33, v33, v66
	s_waitcnt lgkmcnt(14)
	v_add_f32_e32 v34, v34, v67
	s_waitcnt lgkmcnt(13)
	v_add_f32_e32 v35, v35, v68
	s_waitcnt lgkmcnt(12)
	v_add_f32_e32 v36, v36, v69
	s_waitcnt lgkmcnt(11)
	v_add_f32_e32 v37, v37, v70
	s_waitcnt lgkmcnt(10)
	v_add_f32_e32 v38, v38, v71
	s_waitcnt lgkmcnt(9)
	v_add_f32_e32 v39, v39, v72
	s_waitcnt lgkmcnt(8)
	v_add_f32_e32 v40, v40, v73
	s_waitcnt lgkmcnt(7)
	v_add_f32_e32 v41, v41, v74
	s_waitcnt lgkmcnt(6)
	v_add_f32_e32 v42, v42, v75
	s_waitcnt lgkmcnt(5)
	v_add_f32_e32 v43, v43, v76
	s_waitcnt lgkmcnt(4)
	v_add_f32_e32 v44, v44, v77
	s_waitcnt lgkmcnt(3)
	v_add_f32_e32 v45, v45, v78
	s_waitcnt lgkmcnt(2)
	v_add_f32_e32 v46, v46, v0
	s_waitcnt lgkmcnt(1)
	v_add_f32_e32 v47, v47, v1
	s_waitcnt lgkmcnt(0)
	v_add_f32_e32 v48, v48, v2
	ds_bpermute_b32 v66, v23, v33
	ds_bpermute_b32 v67, v23, v34
	ds_bpermute_b32 v68, v23, v35
	ds_bpermute_b32 v69, v23, v36
	ds_bpermute_b32 v70, v23, v37
	ds_bpermute_b32 v71, v23, v38
	ds_bpermute_b32 v72, v23, v39
	ds_bpermute_b32 v73, v23, v40
	ds_bpermute_b32 v74, v23, v41
	ds_bpermute_b32 v75, v23, v42
	ds_bpermute_b32 v76, v23, v43
	ds_bpermute_b32 v77, v23, v44
	ds_bpermute_b32 v78, v23, v45
	ds_bpermute_b32 v0, v23, v46
	ds_bpermute_b32 v1, v23, v47
	ds_bpermute_b32 v2, v23, v48
	s_waitcnt lgkmcnt(15)
	v_add_f32_e32 v33, v33, v66
	s_waitcnt lgkmcnt(14)
	v_add_f32_e32 v34, v34, v67
	s_waitcnt lgkmcnt(13)
	v_add_f32_e32 v35, v35, v68
	s_waitcnt lgkmcnt(12)
	v_add_f32_e32 v36, v36, v69
	s_waitcnt lgkmcnt(11)
	v_add_f32_e32 v37, v37, v70
	s_waitcnt lgkmcnt(10)
	v_add_f32_e32 v38, v38, v71
	s_waitcnt lgkmcnt(9)
	v_add_f32_e32 v39, v39, v72
	s_waitcnt lgkmcnt(8)
	v_add_f32_e32 v40, v40, v73
	s_waitcnt lgkmcnt(7)
	v_add_f32_e32 v41, v41, v74
	s_waitcnt lgkmcnt(6)
	v_add_f32_e32 v42, v42, v75
	s_waitcnt lgkmcnt(5)
	v_add_f32_e32 v43, v43, v76
	s_waitcnt lgkmcnt(4)
	v_add_f32_e32 v44, v44, v77
	s_waitcnt lgkmcnt(3)
	v_add_f32_e32 v45, v45, v78
	s_waitcnt lgkmcnt(2)
	v_add_f32_e32 v46, v46, v0
	s_waitcnt lgkmcnt(1)
	v_add_f32_e32 v47, v47, v1
	s_waitcnt lgkmcnt(0)
	v_add_f32_e32 v48, v48, v2
	ds_bpermute_b32 v66, v24, v33
	ds_bpermute_b32 v67, v24, v34
	ds_bpermute_b32 v68, v24, v35
	ds_bpermute_b32 v69, v24, v36
	ds_bpermute_b32 v70, v24, v37
	ds_bpermute_b32 v71, v24, v38
	ds_bpermute_b32 v72, v24, v39
	ds_bpermute_b32 v73, v24, v40
	ds_bpermute_b32 v74, v24, v41
	ds_bpermute_b32 v75, v24, v42
	ds_bpermute_b32 v76, v24, v43
	ds_bpermute_b32 v77, v24, v44
	ds_bpermute_b32 v78, v24, v45
	ds_bpermute_b32 v0, v24, v46
	ds_bpermute_b32 v1, v24, v47
	ds_bpermute_b32 v2, v24, v48
	s_waitcnt lgkmcnt(15)
	v_add_f32_e32 v33, v33, v66
	s_waitcnt lgkmcnt(14)
	v_add_f32_e32 v34, v34, v67
	s_waitcnt lgkmcnt(13)
	v_add_f32_e32 v35, v35, v68
	s_waitcnt lgkmcnt(12)
	v_add_f32_e32 v36, v36, v69
	s_waitcnt lgkmcnt(11)
	v_add_f32_e32 v37, v37, v70
	s_waitcnt lgkmcnt(10)
	v_add_f32_e32 v38, v38, v71
	s_waitcnt lgkmcnt(9)
	v_add_f32_e32 v39, v39, v72
	s_waitcnt lgkmcnt(8)
	v_add_f32_e32 v40, v40, v73
	s_waitcnt lgkmcnt(7)
	v_add_f32_e32 v41, v41, v74
	s_waitcnt lgkmcnt(6)
	v_add_f32_e32 v42, v42, v75
	s_waitcnt lgkmcnt(5)
	v_add_f32_e32 v43, v43, v76
	s_waitcnt lgkmcnt(4)
	v_add_f32_e32 v44, v44, v77
	s_waitcnt lgkmcnt(3)
	v_add_f32_e32 v45, v45, v78
	s_waitcnt lgkmcnt(2)
	v_add_f32_e32 v46, v46, v0
	s_waitcnt lgkmcnt(1)
	v_add_f32_e32 v47, v47, v1
	s_waitcnt lgkmcnt(0)
	v_add_f32_e32 v48, v48, v2
	ds_bpermute_b32 v66, v25, v33
	ds_bpermute_b32 v67, v25, v34
	ds_bpermute_b32 v68, v25, v35
	ds_bpermute_b32 v69, v25, v36
	ds_bpermute_b32 v70, v25, v37
	ds_bpermute_b32 v71, v25, v38
	ds_bpermute_b32 v72, v25, v39
	ds_bpermute_b32 v73, v25, v40
	ds_bpermute_b32 v74, v25, v41
	ds_bpermute_b32 v75, v25, v42
	ds_bpermute_b32 v76, v25, v43
	ds_bpermute_b32 v77, v25, v44
	ds_bpermute_b32 v78, v25, v45
	ds_bpermute_b32 v0, v25, v46
	ds_bpermute_b32 v1, v25, v47
	ds_bpermute_b32 v2, v25, v48
	s_waitcnt lgkmcnt(15)
	v_add_f32_e32 v33, v33, v66
	s_waitcnt lgkmcnt(14)
	v_add_f32_e32 v34, v34, v67
	s_waitcnt lgkmcnt(13)
	v_add_f32_e32 v35, v35, v68
	s_waitcnt lgkmcnt(12)
	v_add_f32_e32 v36, v36, v69
	s_waitcnt lgkmcnt(11)
	v_add_f32_e32 v37, v37, v70
	s_waitcnt lgkmcnt(10)
	v_add_f32_e32 v38, v38, v71
	s_waitcnt lgkmcnt(9)
	v_add_f32_e32 v39, v39, v72
	s_waitcnt lgkmcnt(8)
	v_add_f32_e32 v40, v40, v73
	s_waitcnt lgkmcnt(7)
	v_add_f32_e32 v41, v41, v74
	s_waitcnt lgkmcnt(6)
	v_add_f32_e32 v42, v42, v75
	s_waitcnt lgkmcnt(5)
	v_add_f32_e32 v43, v43, v76
	s_waitcnt lgkmcnt(4)
	v_add_f32_e32 v44, v44, v77
	s_waitcnt lgkmcnt(3)
; __device__ __forceinline__ float shfl_xor_f(float v, int mask) { const int l = lane_fresh(); return __int_as_float(__builtin_amdgcn_ds_bpermute((l ^ mask) << 2, __float_as_int(v))); }
; __device__ __forceinline__ void ssd_sample_item(const Params& p, int item, const int wv) {
;     ...
;     for (int e = 0; e < 4; ++e) { hn[e] = dA * hv[e] + xp * Bv[e]; yp += hn[e] * Cv[e]; }
;     *(f32x4*)(so + (size_t)pp * 128 + n4) = hn;
; #pragma unroll
;     for (int o = 16; o >= 1; o >>= 1) yp += shfl_xor_f(yp, o);
;     if ((lane & 31) == r) ymine = yp;
	v_add_f32_e32 v45, v45, v78
	s_waitcnt lgkmcnt(2)
	v_add_f32_e32 v46, v46, v0
	s_waitcnt lgkmcnt(1)
	v_add_f32_e32 v47, v47, v1
	s_waitcnt lgkmcnt(0)
	v_add_f32_e32 v48, v48, v2
	ds_bpermute_b32 v66, v26, v33
	ds_bpermute_b32 v67, v26, v34
	ds_bpermute_b32 v68, v26, v35
	ds_bpermute_b32 v69, v26, v36
	ds_bpermute_b32 v70, v26, v37
	ds_bpermute_b32 v71, v26, v38
	ds_bpermute_b32 v72, v26, v39
	ds_bpermute_b32 v73, v26, v40
	ds_bpermute_b32 v74, v26, v41
	ds_bpermute_b32 v75, v26, v42
	ds_bpermute_b32 v76, v26, v43
	ds_bpermute_b32 v77, v26, v44
	ds_bpermute_b32 v78, v26, v45
	ds_bpermute_b32 v0, v26, v46
	ds_bpermute_b32 v1, v26, v47
	ds_bpermute_b32 v2, v26, v48
	s_waitcnt lgkmcnt(15)
	v_add_f32_e32 v33, v33, v66
	s_waitcnt lgkmcnt(14)
	v_add_f32_e32 v34, v34, v67
	s_waitcnt lgkmcnt(13)
	v_add_f32_e32 v35, v35, v68
	s_waitcnt lgkmcnt(12)
	v_add_f32_e32 v36, v36, v69
	s_waitcnt lgkmcnt(11)
	v_add_f32_e32 v37, v37, v70
	s_waitcnt lgkmcnt(10)
	v_add_f32_e32 v38, v38, v71
	s_waitcnt lgkmcnt(9)
	v_add_f32_e32 v39, v39, v72
	s_waitcnt lgkmcnt(8)
	v_add_f32_e32 v40, v40, v73
	s_waitcnt lgkmcnt(7)
	v_add_f32_e32 v41, v41, v74
	s_waitcnt lgkmcnt(6)
	v_add_f32_e32 v42, v42, v75
	s_waitcnt lgkmcnt(5)
	v_add_f32_e32 v43, v43, v76
	s_waitcnt lgkmcnt(4)
	v_add_f32_e32 v44, v44, v77
	s_waitcnt lgkmcnt(3)
	v_add_f32_e32 v45, v45, v78
	s_waitcnt lgkmcnt(2)
	v_add_f32_e32 v46, v46, v0
	s_waitcnt lgkmcnt(1)
	v_add_f32_e32 v47, v47, v1
	s_waitcnt lgkmcnt(0)
	v_add_f32_e32 v48, v48, v2
	ds_bpermute_b32 v66, v22, v49
	ds_bpermute_b32 v67, v22, v50
	ds_bpermute_b32 v68, v22, v51
	ds_bpermute_b32 v69, v22, v52
	ds_bpermute_b32 v70, v22, v53
	ds_bpermute_b32 v71, v22, v54
	ds_bpermute_b32 v72, v22, v55
	ds_bpermute_b32 v73, v22, v56
	ds_bpermute_b32 v74, v22, v57
	ds_bpermute_b32 v75, v22, v58
	ds_bpermute_b32 v76, v22, v59
	ds_bpermute_b32 v77, v22, v60
	ds_bpermute_b32 v78, v22, v61
	ds_bpermute_b32 v0, v22, v62
	ds_bpermute_b32 v1, v22, v63
	ds_bpermute_b32 v2, v22, v64
	s_waitcnt lgkmcnt(15)
	v_add_f32_e32 v49, v49, v66
	s_waitcnt lgkmcnt(14)
	v_add_f32_e32 v50, v50, v67
	s_waitcnt lgkmcnt(13)
	v_add_f32_e32 v51, v51, v68
	s_waitcnt lgkmcnt(12)
	v_add_f32_e32 v52, v52, v69
	s_waitcnt lgkmcnt(11)
	v_add_f32_e32 v53, v53, v70
	s_waitcnt lgkmcnt(10)
	v_add_f32_e32 v54, v54, v71
	s_waitcnt lgkmcnt(9)
	v_add_f32_e32 v55, v55, v72
	s_waitcnt lgkmcnt(8)
	v_add_f32_e32 v56, v56, v73
	s_waitcnt lgkmcnt(7)
	v_add_f32_e32 v57, v57, v74
	s_waitcnt lgkmcnt(6)
	v_add_f32_e32 v58, v58, v75
	s_waitcnt lgkmcnt(5)
	v_add_f32_e32 v59, v59, v76
	s_waitcnt lgkmcnt(4)
	v_add_f32_e32 v60, v60, v77
	s_waitcnt lgkmcnt(3)
	v_add_f32_e32 v61, v61, v78
	s_waitcnt lgkmcnt(2)
	v_add_f32_e32 v62, v62, v0
	s_waitcnt lgkmcnt(1)
	v_add_f32_e32 v63, v63, v1
	s_waitcnt lgkmcnt(0)
	v_add_f32_e32 v64, v64, v2
	ds_bpermute_b32 v66, v23, v49
	ds_bpermute_b32 v67, v23, v50
	ds_bpermute_b32 v68, v23, v51
	ds_bpermute_b32 v69, v23, v52
	ds_bpermute_b32 v70, v23, v53
	ds_bpermute_b32 v71, v23, v54
	ds_bpermute_b32 v72, v23, v55
	ds_bpermute_b32 v73, v23, v56
	ds_bpermute_b32 v74, v23, v57
	ds_bpermute_b32 v75, v23, v58
	ds_bpermute_b32 v76, v23, v59
	ds_bpermute_b32 v77, v23, v60
	ds_bpermute_b32 v78, v23, v61
	ds_bpermute_b32 v0, v23, v62
	ds_bpermute_b32 v1, v23, v63
	ds_bpermute_b32 v2, v23, v64
	s_waitcnt lgkmcnt(15)
	v_add_f32_e32 v49, v49, v66
	s_waitcnt lgkmcnt(14)
	v_add_f32_e32 v50, v50, v67
	s_waitcnt lgkmcnt(13)
	v_add_f32_e32 v51, v51, v68
	s_waitcnt lgkmcnt(12)
	v_add_f32_e32 v52, v52, v69
	s_waitcnt lgkmcnt(11)
	v_add_f32_e32 v53, v53, v70
	s_waitcnt lgkmcnt(10)
	v_add_f32_e32 v54, v54, v71
	s_waitcnt lgkmcnt(9)
	v_add_f32_e32 v55, v55, v72
	s_waitcnt lgkmcnt(8)
	v_add_f32_e32 v56, v56, v73
	s_waitcnt lgkmcnt(7)
	v_add_f32_e32 v57, v57, v74
	s_waitcnt lgkmcnt(6)
	v_add_f32_e32 v58, v58, v75
	s_waitcnt lgkmcnt(5)
	v_add_f32_e32 v59, v59, v76
	s_waitcnt lgkmcnt(4)
	v_add_f32_e32 v60, v60, v77
	s_waitcnt lgkmcnt(3)
	v_add_f32_e32 v61, v61, v78
	s_waitcnt lgkmcnt(2)
	v_add_f32_e32 v62, v62, v0
	s_waitcnt lgkmcnt(1)
	v_add_f32_e32 v63, v63, v1
	s_waitcnt lgkmcnt(0)
	v_add_f32_e32 v64, v64, v2
	ds_bpermute_b32 v66, v24, v49
	ds_bpermute_b32 v67, v24, v50
	ds_bpermute_b32 v68, v24, v51
	ds_bpermute_b32 v69, v24, v52
	ds_bpermute_b32 v70, v24, v53
	ds_bpermute_b32 v71, v24, v54
	ds_bpermute_b32 v72, v24, v55
	ds_bpermute_b32 v73, v24, v56
	ds_bpermute_b32 v74, v24, v57
	ds_bpermute_b32 v75, v24, v58
	ds_bpermute_b32 v76, v24, v59
	ds_bpermute_b32 v77, v24, v60
	ds_bpermute_b32 v78, v24, v61
	ds_bpermute_b32 v0, v24, v62
	ds_bpermute_b32 v1, v24, v63
	ds_bpermute_b32 v2, v24, v64
	s_waitcnt lgkmcnt(15)
	v_add_f32_e32 v49, v49, v66
	s_waitcnt lgkmcnt(14)
	v_add_f32_e32 v50, v50, v67
	s_waitcnt lgkmcnt(13)
	v_add_f32_e32 v51, v51, v68
	s_waitcnt lgkmcnt(12)
	v_add_f32_e32 v52, v52, v69
	s_waitcnt lgkmcnt(11)
	v_add_f32_e32 v53, v53, v70
	s_waitcnt lgkmcnt(10)
	v_add_f32_e32 v54, v54, v71
	s_waitcnt lgkmcnt(9)
	v_add_f32_e32 v55, v55, v72
	s_waitcnt lgkmcnt(8)
	v_add_f32_e32 v56, v56, v73
	s_waitcnt lgkmcnt(7)
	v_add_f32_e32 v57, v57, v74
	s_waitcnt lgkmcnt(6)
	v_add_f32_e32 v58, v58, v75
	s_waitcnt lgkmcnt(5)
	v_add_f32_e32 v59, v59, v76
	s_waitcnt lgkmcnt(4)
	v_add_f32_e32 v60, v60, v77
	s_waitcnt lgkmcnt(3)
	v_add_f32_e32 v61, v61, v78
	s_waitcnt lgkmcnt(2)
	v_add_f32_e32 v62, v62, v0
	s_waitcnt lgkmcnt(1)
	v_add_f32_e32 v63, v63, v1
	s_waitcnt lgkmcnt(0)
; __device__ __forceinline__ float shfl_xor_f(float v, int mask) { const int l = lane_fresh(); return __int_as_float(__builtin_amdgcn_ds_bpermute((l ^ mask) << 2, __float_as_int(v))); }
; __device__ __forceinline__ void ssd_sample_item(const Params& p, int item, const int wv) {
;     ...
;     for (int e = 0; e < 4; ++e) { hn[e] = dA * hv[e] + xp * Bv[e]; yp += hn[e] * Cv[e]; }
;     *(f32x4*)(so + (size_t)pp * 128 + n4) = hn;
; #pragma unroll
;     for (int o = 16; o >= 1; o >>= 1) yp += shfl_xor_f(yp, o);
;     if ((lane & 31) == r) ymine = yp;
	v_add_f32_e32 v64, v64, v2
	ds_bpermute_b32 v66, v25, v49
	ds_bpermute_b32 v67, v25, v50
	ds_bpermute_b32 v68, v25, v51
	ds_bpermute_b32 v69, v25, v52
	ds_bpermute_b32 v70, v25, v53
	ds_bpermute_b32 v71, v25, v54
	ds_bpermute_b32 v72, v25, v55
	ds_bpermute_b32 v73, v25, v56
	ds_bpermute_b32 v74, v25, v57
	ds_bpermute_b32 v75, v25, v58
	ds_bpermute_b32 v76, v25, v59
	ds_bpermute_b32 v77, v25, v60
	ds_bpermute_b32 v78, v25, v61
	ds_bpermute_b32 v0, v25, v62
	ds_bpermute_b32 v1, v25, v63
	ds_bpermute_b32 v2, v25, v64
	s_waitcnt lgkmcnt(15)
	v_add_f32_e32 v49, v49, v66
	s_waitcnt lgkmcnt(14)
	v_add_f32_e32 v50, v50, v67
	s_waitcnt lgkmcnt(13)
	v_add_f32_e32 v51, v51, v68
	s_waitcnt lgkmcnt(12)
	v_add_f32_e32 v52, v52, v69
	s_waitcnt lgkmcnt(11)
	v_add_f32_e32 v53, v53, v70
	s_waitcnt lgkmcnt(10)
	v_add_f32_e32 v54, v54, v71
	s_waitcnt lgkmcnt(9)
	v_add_f32_e32 v55, v55, v72
	s_waitcnt lgkmcnt(8)
	v_add_f32_e32 v56, v56, v73
	s_waitcnt lgkmcnt(7)
	v_add_f32_e32 v57, v57, v74
	s_waitcnt lgkmcnt(6)
	v_add_f32_e32 v58, v58, v75
	s_waitcnt lgkmcnt(5)
	v_add_f32_e32 v59, v59, v76
	s_waitcnt lgkmcnt(4)
	v_add_f32_e32 v60, v60, v77
	s_waitcnt lgkmcnt(3)
	v_add_f32_e32 v61, v61, v78
	s_waitcnt lgkmcnt(2)
	v_add_f32_e32 v62, v62, v0
	s_waitcnt lgkmcnt(1)
	v_add_f32_e32 v63, v63, v1
	s_waitcnt lgkmcnt(0)
	v_add_f32_e32 v64, v64, v2
	ds_bpermute_b32 v66, v26, v49
	ds_bpermute_b32 v67, v26, v50
	ds_bpermute_b32 v68, v26, v51
	ds_bpermute_b32 v69, v26, v52
	ds_bpermute_b32 v70, v26, v53
	ds_bpermute_b32 v71, v26, v54
	ds_bpermute_b32 v72, v26, v55
	ds_bpermute_b32 v73, v26, v56
	ds_bpermute_b32 v74, v26, v57
	ds_bpermute_b32 v75, v26, v58
	ds_bpermute_b32 v76, v26, v59
	ds_bpermute_b32 v77, v26, v60
	ds_bpermute_b32 v78, v26, v61
	ds_bpermute_b32 v0, v26, v62
	ds_bpermute_b32 v1, v26, v63
	ds_bpermute_b32 v2, v26, v64
	s_waitcnt lgkmcnt(15)
	v_add_f32_e32 v49, v49, v66
	s_waitcnt lgkmcnt(14)
	v_add_f32_e32 v50, v50, v67
	s_waitcnt lgkmcnt(13)
	v_add_f32_e32 v51, v51, v68
	s_waitcnt lgkmcnt(12)
	v_add_f32_e32 v52, v52, v69
	s_waitcnt lgkmcnt(11)
	v_add_f32_e32 v53, v53, v70
	s_waitcnt lgkmcnt(10)
	v_add_f32_e32 v54, v54, v71
	s_waitcnt lgkmcnt(9)
	v_add_f32_e32 v55, v55, v72
	s_waitcnt lgkmcnt(8)
	v_add_f32_e32 v56, v56, v73
	s_waitcnt lgkmcnt(7)
	v_add_f32_e32 v57, v57, v74
	s_waitcnt lgkmcnt(6)
	v_add_f32_e32 v58, v58, v75
	s_waitcnt lgkmcnt(5)
	v_add_f32_e32 v59, v59, v76
	s_waitcnt lgkmcnt(4)
	v_add_f32_e32 v60, v60, v77
	s_waitcnt lgkmcnt(3)
	v_add_f32_e32 v61, v61, v78
	s_waitcnt lgkmcnt(2)
	v_add_f32_e32 v62, v62, v0
	s_waitcnt lgkmcnt(1)
	v_add_f32_e32 v63, v63, v1
	s_waitcnt lgkmcnt(0)
; __device__ __forceinline__ u16 f2bf(float f) { return (u16)(cvt_pk(f, 0.f) & 0xffffu); }
; __device__ __forceinline__ float bf2f(u16 h) { return __uint_as_float(((unsigned)h) << 16); }
; __device__ __forceinline__ float shfl_idx_f(float v, int src) { return __int_as_float(__builtin_amdgcn_ds_bpermute(src << 2, __float_as_int(v))); }
; __device__ __forceinline__ void ssd_sample_item(const Params& p, int item, const int wv) {
;     ...
;     if ((lane & 31) == r) ymine = yp;
;   }
;   const int pm = 2 * (lane & 31) + hf;
;   const float xm = shfl_idx_f(x, pm);
;   const float zs = bf2f(ZS[(size_t)tok * 1024 + h * 64 + pm]);
;   const float yg = (ymine + xm * p.in[17][h]) * zs;
;   float ss = wave_sum(yg * yg);
;   Y[(size_t)tok * 1024 + h * 64 + pm] = f2bf(yg);
;   if (lane == 0) { YPS[(size_t)tok * 32 + g * 16 + (h & 7) * 2] = ss; YPS[(size_t)tok * 32 + g * 16 + (h & 7) * 2 + 1] = 0.f; }
	v_add_f32_e32 v64, v64, v2
	v_cmp_eq_u32_e64 s[36:37], 0, v29
	v_cmp_eq_u32_e64 s[38:39], 1, v29
	v_cmp_eq_u32_e64 s[40:41], 2, v29
	v_cndmask_b32_e64 v17, v17, v33, s[36:37]
	v_cmp_eq_u32_e64 s[36:37], 3, v29
	v_cndmask_b32_e64 v17, v17, v34, s[38:39]
	v_cmp_eq_u32_e64 s[38:39], 4, v29
	v_cndmask_b32_e64 v17, v17, v35, s[40:41]
	v_cmp_eq_u32_e64 s[40:41], 5, v29
	v_cndmask_b32_e64 v17, v17, v36, s[36:37]
	v_cmp_eq_u32_e64 s[36:37], 6, v29
	v_cndmask_b32_e64 v17, v17, v37, s[38:39]
	v_cmp_eq_u32_e64 s[38:39], 7, v29
	v_cndmask_b32_e64 v17, v17, v38, s[40:41]
	v_cmp_eq_u32_e64 s[40:41], 8, v29
	v_cndmask_b32_e64 v17, v17, v39, s[36:37]
	v_cmp_eq_u32_e64 s[36:37], 9, v29
	v_cndmask_b32_e64 v17, v17, v40, s[38:39]
	v_cmp_eq_u32_e64 s[38:39], 10, v29
	v_cndmask_b32_e64 v17, v17, v41, s[40:41]
	v_cmp_eq_u32_e64 s[40:41], 11, v29
	v_cndmask_b32_e64 v17, v17, v42, s[36:37]
	v_cmp_eq_u32_e64 s[36:37], 12, v29
	v_cndmask_b32_e64 v17, v17, v43, s[38:39]
	v_cmp_eq_u32_e64 s[38:39], 13, v29
	v_cndmask_b32_e64 v17, v17, v44, s[40:41]
	v_cmp_eq_u32_e64 s[40:41], 14, v29
	v_cndmask_b32_e64 v17, v17, v45, s[36:37]
	v_cmp_eq_u32_e64 s[36:37], 15, v29
	v_cndmask_b32_e64 v17, v17, v46, s[38:39]
	v_cmp_eq_u32_e64 s[38:39], 16, v29
	v_cndmask_b32_e64 v17, v17, v47, s[40:41]
	v_cmp_eq_u32_e64 s[40:41], 17, v29
	v_cndmask_b32_e64 v17, v17, v48, s[36:37]
	v_cmp_eq_u32_e64 s[36:37], 18, v29
	v_cndmask_b32_e64 v17, v17, v49, s[38:39]
	v_cmp_eq_u32_e64 s[38:39], 19, v29
	v_cndmask_b32_e64 v17, v17, v50, s[40:41]
	v_cmp_eq_u32_e64 s[40:41], 20, v29
	v_cndmask_b32_e64 v17, v17, v51, s[36:37]
	v_cmp_eq_u32_e64 s[36:37], 21, v29
	v_cndmask_b32_e64 v17, v17, v52, s[38:39]
	v_cmp_eq_u32_e64 s[38:39], 22, v29
	v_cndmask_b32_e64 v17, v17, v53, s[40:41]
	v_cmp_eq_u32_e64 s[40:41], 23, v29
	v_cndmask_b32_e64 v17, v17, v54, s[36:37]
	v_cmp_eq_u32_e64 s[36:37], 24, v29
	v_cndmask_b32_e64 v17, v17, v55, s[38:39]
	v_cmp_eq_u32_e64 s[38:39], 25, v29
	v_cndmask_b32_e64 v17, v17, v56, s[40:41]
	v_cmp_eq_u32_e64 s[40:41], 26, v29
	v_cndmask_b32_e64 v17, v17, v57, s[36:37]
	v_cmp_eq_u32_e64 s[36:37], 27, v29
	v_cndmask_b32_e64 v17, v17, v58, s[38:39]
	v_cmp_eq_u32_e64 s[38:39], 28, v29
	v_cndmask_b32_e64 v17, v17, v59, s[40:41]
	v_cmp_eq_u32_e64 s[40:41], 29, v29
	v_cndmask_b32_e64 v17, v17, v60, s[36:37]
	v_cmp_eq_u32_e64 s[36:37], 30, v29
	v_cndmask_b32_e64 v17, v17, v61, s[38:39]
	v_cmp_eq_u32_e64 s[38:39], 31, v29
	v_cndmask_b32_e64 v17, v17, v62, s[40:41]
	s_nop 1
	v_cndmask_b32_e64 v17, v17, v63, s[36:37]
	v_cndmask_b32_e64 v17, v17, v64, s[38:39]
	v_add_u32_e32 v32, 0x100, v32
	s_mov_b32 s10, 32
	s_mov_b64 s[12:13], 0x8000
	s_lshl_b32 s10, s31, 11
	s_add_u32 s0, s17, s10
	v_lshl_add_u32 v0, v29, 1, v16
	s_addc_u32 s1, s18, 0
	s_lshl_b32 s12, s34, 1
	v_ashrrev_i32_e32 v1, 31, v0
	s_add_u32 s0, s0, s12
	s_addc_u32 s1, s1, 0
	v_lshlrev_b64 v[2:3], 1, v[0:1]
	v_lshl_add_u64 v[6:7], s[0:1], 0, v[2:3]
	s_lshl_b32 s0, s33, 2
	v_readlane_b32 s60, v251, 22
	v_mov_b32_e32 v4, s0
	v_readlane_b32 s62, v251, 24
	v_readlane_b32 s63, v251, 25
	global_load_ushort v1, v[6:7], off
	v_lshlrev_b32_e32 v0, 2, v0
	ds_bpermute_b32 v0, v0, v31
	s_add_u32 s0, s48, s10
	s_addc_u32 s1, s49, 0
	global_load_dword v4, v4, s[62:63]
	v_mbcnt_lo_u32_b32 v6, -1, 0
	v_mbcnt_hi_u32_b32 v6, -1, v6
	v_cmp_eq_u32_e32 vcc, 0, v28
	v_lshlrev_b32_e32 v6, 2, v6
	v_xor_b32_e32 v6, 0x80, v6
	v_readlane_b32 s61, v251, 23
	v_readlane_b32 s64, v251, 26
	v_readlane_b32 s65, v251, 27
	v_readlane_b32 s66, v251, 28
	v_readlane_b32 s67, v251, 29
	v_readlane_b32 s68, v251, 30
	v_readlane_b32 s69, v251, 31
	v_readlane_b32 s70, v251, 32
	v_readlane_b32 s71, v251, 33
	v_readlane_b32 s72, v251, 34
	v_readlane_b32 s73, v251, 35
	v_readlane_b32 s74, v251, 36
	v_readlane_b32 s75, v251, 37
	s_waitcnt vmcnt(1)
	v_lshlrev_b32_e32 v1, 16, v1
	s_waitcnt vmcnt(0) lgkmcnt(0)
	v_fmac_f32_e32 v17, v4, v0
	v_mul_f32_e32 v0, v17, v1
	v_mul_f32_e32 v1, v0, v0
	ds_bpermute_b32 v1, v6, v1
	v_mbcnt_lo_u32_b32 v4, -1, 0
	v_mbcnt_hi_u32_b32 v4, -1, v4
	s_waitcnt lgkmcnt(0)
	v_fmac_f32_e32 v1, v0, v0
	v_lshlrev_b32_e32 v4, 2, v4
	v_xor_b32_e32 v4, 64, v4
	ds_bpermute_b32 v4, v4, v1
	s_waitcnt lgkmcnt(0)
	v_add_f32_e32 v1, v1, v4
	s_nop 1
	v_mov_b32_dpp v4, v1 row_ror:8 row_mask:0xf bank_mask:0xf
	s_waitcnt lgkmcnt(0)
	v_add_f32_e32 v1, v1, v4
	s_nop 1
	v_mov_b32_dpp v4, v1 row_shl:4 row_mask:0xf bank_mask:0x5
	v_mov_b32_dpp v4, v1 row_shr:4 row_mask:0xf bank_mask:0xa
	v_mbcnt_lo_u32_b32 v7, -1, 0
	v_mbcnt_hi_u32_b32 v7, -1, v7
	s_waitcnt lgkmcnt(0)
	v_add_f32_e32 v1, v1, v4
	s_nop 1
	v_mov_b32_dpp v4, v1 quad_perm:[2,3,0,1] row_mask:0xf bank_mask:0xf
	v_lshlrev_b32_e32 v6, 2, v7
	v_xor_b32_e32 v6, 4, v6
	v_cvt_pk_bf16_f32 v7, v0, s0
	s_add_u32 s0, s0, s12
	s_waitcnt lgkmcnt(0)
	v_add_f32_e32 v0, v1, v4
	s_nop 1
	v_mov_b32_dpp v1, v0 quad_perm:[1,0,3,2] row_mask:0xf bank_mask:0xf
	s_addc_u32 s1, s1, 0
	v_lshl_add_u64 v[2:3], s[0:1], 0, v[2:3]
	global_store_short v[2:3], v7, off
	s_and_saveexec_b64 s[0:1], vcc
	s_cbranch_execz .LBB0_455
	s_lshl_b32 s10, s31, 7
	s_add_u32 s10, s19, s10
	s_addc_u32 s13, s20, 0
	s_lshl_b32 s12, s30, 6
	s_add_u32 s12, s10, s12
	s_addc_u32 s13, s13, 0
	s_lshl_b32 s10, s29, 3
	s_and_b32 s10, s10, 56
	s_waitcnt lgkmcnt(0)
	v_add_f32_e32 v4, v0, v1
	v_mov_b32_e32 v0, s10
	global_store_dwordx2 v0, v[4:5], s[12:13]
	s_branch .LBB0_455

; __device__ __forceinline__ float bflo(unsigned w) { return __uint_as_float(w << 16); }
; __device__ __forceinline__ float bfhi(unsigned w) { return __uint_as_float(w & 0xffff0000u); }
; __device__ __forceinline__ void attn_sample_item(const Params& p, int item, const int wv) {
;     ...
;   const float* Kc = p.in[3] + ((size_t)b * 256 * 4 + h) * 128;
;   const float* Vc = p.in[4] + ((size_t)b * 256 * 4 + h) * 128;
;   const int vdch = tid & 31, vmg = tid >> 5;
;   f32x4 vreg[16];
; #pragma unroll
;   for (int i = 0; i < 16; ++i) vreg[i] = *(const f32x4*)(Vc + (size_t)(vmg * 16 + i) * 512 + vdch * 4);
;   __syncthreads();
;   {
;     const int dch = lane & 15, ksub = lane >> 4;
;     u32x4 qw = *(const u32x4*)(Q + (size_t)tok * 512 + h * 128 + dch * 8);
;     float q[8] = {bflo(qw.x), bfhi(qw.x), bflo(qw.y), bfhi(qw.y), bflo(qw.z), bfhi(qw.z), bflo(qw.w), bfhi(qw.w)};
; #pragma unroll
;     for (int it = 0; it < 8; ++it) {
;       const int mm = wid * 32 + it * 4 + ksub;
;       f32x4 k0 = *(const f32x4*)(Kc + (size_t)mm * 512 + dch * 8), k1 = *(const f32x4*)(Kc + (size_t)mm * 512 + dch * 8 + 4);
;       float d = q[0] * k0[0] + q[1] * k0[1] + q[2] * k0[2] + q[3] * k0[3] + q[4] * k1[0] + q[5] * k1[1] + q[6] * k1[2] + q[7] * k1[3];
.LBB0_464:
	s_ashr_i32 s0, s19, 2
	s_ashr_i32 s1, s0, 31
	s_and_b32 s22, s15, 0x180
	v_readlane_b32 s64, v251, 6
	s_lshl_b64 s[10:11], s[0:1], 19
	s_lshl_b32 s1, s22, 2
	v_readlane_b32 s72, v251, 14
	v_readlane_b32 s73, v251, 15
	s_or_b32 s1, s10, s1
	s_mov_b64 s[44:45], s[72:73]
	v_readlane_b32 s70, v251, 12
	v_readlane_b32 s71, v251, 13
	s_add_u32 s20, s44, s1
	v_mbcnt_lo_u32_b32 v72, -1, 0
	v_mbcnt_hi_u32_b32 v72, -1, v72
	s_mov_b64 s[42:43], s[70:71]
	v_add_u32_e32 v66, s82, v72
	s_addc_u32 s21, s45, s11
	s_addk_i32 s0, 0x4000
	v_and_b32_e32 v0, 31, v72
	v_ashrrev_i32_e32 v67, 5, v66
	s_add_u32 s10, s42, s1
	v_lshlrev_b32_e32 v56, 4, v67
	v_lshlrev_b32_e32 v64, 4, v0
	s_addc_u32 s11, s43, s11
	s_ashr_i32 s1, s0, 31
	v_lshl_add_u64 v[58:59], s[20:21], 0, v[64:65]
	v_ashrrev_i32_e32 v57, 31, v56
	s_lshl_b64 s[20:21], s[0:1], 10
	s_waitcnt lgkmcnt(0)
	v_lshlrev_b64 v[0:1], 11, v[56:57]
	v_or_b32_e32 v2, 1, v56
	v_or_b32_e32 v8, 2, v56
	v_or_b32_e32 v10, 3, v56
	v_or_b32_e32 v16, 4, v56
	v_or_b32_e32 v18, 5, v56
	v_or_b32_e32 v24, 6, v56
	v_or_b32_e32 v26, 7, v56
	v_or_b32_e32 v32, 8, v56
	v_or_b32_e32 v34, 9, v56
	v_or_b32_e32 v40, 10, v56
	v_or_b32_e32 v42, 11, v56
	v_or_b32_e32 v48, 12, v56
	v_or_b32_e32 v50, 13, v56
	v_or_b32_e32 v60, 14, v56
	v_or_b32_e32 v56, 15, v56
	s_add_u32 s23, s7, s20
	v_ashrrev_i32_e32 v3, 31, v2
	v_ashrrev_i32_e32 v9, 31, v8
	v_ashrrev_i32_e32 v11, 31, v10
	v_ashrrev_i32_e32 v17, 31, v16
	v_ashrrev_i32_e32 v19, 31, v18
	v_ashrrev_i32_e32 v25, 31, v24
	v_ashrrev_i32_e32 v27, 31, v26
	v_ashrrev_i32_e32 v33, 31, v32
	v_ashrrev_i32_e32 v35, 31, v34
	v_ashrrev_i32_e32 v41, 31, v40
	v_ashrrev_i32_e32 v43, 31, v42
	v_ashrrev_i32_e32 v49, 31, v48
	v_ashrrev_i32_e32 v51, 31, v50
	v_ashrrev_i32_e32 v61, 31, v60
	v_ashrrev_i32_e32 v57, 31, v56
	s_addc_u32 s21, s12, s21
	s_lshl_b32 s20, s22, 1
	v_lshlrev_b64 v[2:3], 11, v[2:3]
	v_lshlrev_b64 v[8:9], 11, v[8:9]
	v_lshlrev_b64 v[10:11], 11, v[10:11]
	v_lshlrev_b64 v[16:17], 11, v[16:17]
	v_lshlrev_b64 v[18:19], 11, v[18:19]
	v_lshlrev_b64 v[24:25], 11, v[24:25]
	v_lshlrev_b64 v[26:27], 11, v[26:27]
	v_lshlrev_b64 v[32:33], 11, v[32:33]
	v_lshlrev_b64 v[34:35], 11, v[34:35]
	v_lshlrev_b64 v[40:41], 11, v[40:41]
	v_lshlrev_b64 v[42:43], 11, v[42:43]
	v_lshlrev_b64 v[48:49], 11, v[48:49]
	v_lshlrev_b64 v[50:51], 11, v[50:51]
	v_lshlrev_b64 v[60:61], 11, v[60:61]
	v_lshlrev_b64 v[56:57], 11, v[56:57]
	v_and_b32_e32 v92, 15, v72
	v_ashrrev_i32_e32 v68, 4, v72
	s_add_u32 s22, s23, s20
	v_lshl_add_u64 v[0:1], v[58:59], 0, v[0:1]
	v_lshl_add_u64 v[2:3], v[58:59], 0, v[2:3]
	v_lshl_add_u64 v[8:9], v[58:59], 0, v[8:9]
	v_lshl_add_u64 v[10:11], v[58:59], 0, v[10:11]
	v_lshl_add_u64 v[16:17], v[58:59], 0, v[16:17]
	v_lshl_add_u64 v[18:19], v[58:59], 0, v[18:19]
	v_lshl_add_u64 v[24:25], v[58:59], 0, v[24:25]
	v_lshl_add_u64 v[26:27], v[58:59], 0, v[26:27]
	v_lshl_add_u64 v[32:33], v[58:59], 0, v[32:33]
	v_lshl_add_u64 v[34:35], v[58:59], 0, v[34:35]
	v_lshl_add_u64 v[40:41], v[58:59], 0, v[40:41]
	v_lshl_add_u64 v[42:43], v[58:59], 0, v[42:43]
	v_lshl_add_u64 v[48:49], v[58:59], 0, v[48:49]
	v_lshl_add_u64 v[50:51], v[58:59], 0, v[50:51]
	v_lshl_add_u64 v[60:61], v[58:59], 0, v[60:61]
	v_lshl_add_u64 v[56:57], v[58:59], 0, v[56:57]
	s_addc_u32 s23, s21, 0
	v_lshlrev_b32_e32 v69, 4, v92
	v_add_u32_e32 v70, s5, v68
	global_load_dwordx4 v[4:7], v[0:1], off
	s_nop 0
	global_load_dwordx4 v[0:3], v[2:3], off
	s_nop 0
	global_load_dwordx4 v[12:15], v[8:9], off
	s_nop 0
	global_load_dwordx4 v[8:11], v[10:11], off
	s_nop 0
	global_load_dwordx4 v[20:23], v[16:17], off
	s_nop 0
	global_load_dwordx4 v[16:19], v[18:19], off
	s_nop 0
	global_load_dwordx4 v[28:31], v[24:25], off
	s_nop 0
	global_load_dwordx4 v[24:27], v[26:27], off
	s_nop 0
	global_load_dwordx4 v[36:39], v[32:33], off
	s_nop 0
	global_load_dwordx4 v[32:35], v[34:35], off
	s_nop 0
	global_load_dwordx4 v[44:47], v[40:41], off
	s_nop 0
	global_load_dwordx4 v[40:43], v[42:43], off
	s_nop 0
	global_load_dwordx4 v[52:55], v[48:49], off
	s_nop 0
	global_load_dwordx4 v[48:51], v[50:51], off
	s_nop 0
	global_load_dwordx4 v[60:63], v[60:61], off
	s_nop 0
	global_load_dwordx4 v[56:59], v[56:57], off
	s_barrier
	global_load_dwordx4 v[80:83], v69, s[22:23]
	v_lshlrev_b32_e32 v68, 5, v92
	v_mov_b32_e32 v69, v65
	v_ashrrev_i32_e32 v71, 31, v70
	v_lshl_add_u64 v[68:69], s[10:11], 0, v[68:69]
	v_lshlrev_b64 v[74:75], 11, v[70:71]
	v_lshl_add_u64 v[74:75], v[68:69], 0, v[74:75]
	global_load_dwordx4 v[84:87], v[74:75], off
	global_load_dwordx4 v[88:91], v[74:75], off offset:16
	v_mov_b32_e32 v221, 0
	v_mov_b32_e32 v220, 0x2000
	v_lshl_add_u64 v[222:223], v[220:221], 0, v[74:75]
	global_load_dwordx4 v[164:167], v[222:223], off
	global_load_dwordx4 v[168:171], v[222:223], off offset:16
	v_mov_b32_e32 v220, 0x4000
	v_lshl_add_u64 v[222:223], v[220:221], 0, v[74:75]
	global_load_dwordx4 v[172:175], v[222:223], off
	global_load_dwordx4 v[176:179], v[222:223], off offset:16
	v_mov_b32_e32 v220, 0x6000
	v_lshl_add_u64 v[222:223], v[220:221], 0, v[74:75]
	global_load_dwordx4 v[180:183], v[222:223], off
	global_load_dwordx4 v[184:187], v[222:223], off offset:16
	v_mov_b32_e32 v220, 0x8000
	v_lshl_add_u64 v[222:223], v[220:221], 0, v[74:75]
	global_load_dwordx4 v[188:191], v[222:223], off
	global_load_dwordx4 v[192:195], v[222:223], off offset:16
	v_mov_b32_e32 v220, 0xa000
	v_lshl_add_u64 v[222:223], v[220:221], 0, v[74:75]
	global_load_dwordx4 v[196:199], v[222:223], off
	global_load_dwordx4 v[200:203], v[222:223], off offset:16
	v_mov_b32_e32 v220, 0xc000
	v_lshl_add_u64 v[222:223], v[220:221], 0, v[74:75]
	global_load_dwordx4 v[204:207], v[222:223], off
	global_load_dwordx4 v[208:211], v[222:223], off offset:16
	v_mov_b32_e32 v220, 0xe000
	v_lshl_add_u64 v[222:223], v[220:221], 0, v[74:75]
	global_load_dwordx4 v[212:215], v[222:223], off
	global_load_dwordx4 v[216:219], v[222:223], off offset:16
	v_cmp_eq_u32_e32 vcc, 0, v92
	v_readlane_b32 s65, v251, 7
	v_readlane_b32 s66, v251, 8
	v_readlane_b32 s67, v251, 9
	v_readlane_b32 s68, v251, 10
	v_readlane_b32 s69, v251, 11
	v_readlane_b32 s74, v251, 16
	v_readlane_b32 s75, v251, 17
	v_readlane_b32 s76, v251, 18
	v_readlane_b32 s77, v251, 19
	v_readlane_b32 s78, v251, 20
	v_readlane_b32 s79, v251, 21
	s_waitcnt vmcnt(16)
; __device__ __forceinline__ float shfl_xor_f(float v, int mask) { const int l = lane_fresh(); return __int_as_float(__builtin_amdgcn_ds_bpermute((l ^ mask) << 2, __float_as_int(v))); }
; __device__ __forceinline__ void attn_sample_item(const Params& p, int item, const int wv) {
;     ...
;     for (int it = 0; it < 8; ++it) {
;       const int mm = wid * 32 + it * 4 + ksub;
;       f32x4 k0 = *(const f32x4*)(Kc + (size_t)mm * 512 + dch * 8), k1 = *(const f32x4*)(Kc + (size_t)mm * 512 + dch * 8 + 4);
;       float d = q[0] * k0[0] + q[1] * k0[1] + q[2] * k0[2] + q[3] * k0[3] + q[4] * k1[0] + q[5] * k1[1] + q[6] * k1[2] + q[7] * k1[3];
;       d += shfl_xor_f(d, 1); d += shfl_xor_f(d, 2); d += shfl_xor_f(d, 4); d += shfl_xor_f(d, 8);
;       if (dch == 0) sc_l[mm] = d * 0.08838834764831845f;
;     }
	v_and_b32_e32 v79, 0xffff0000, v80
	v_lshlrev_b32_e32 v71, 16, v80
	v_lshlrev_b32_e32 v73, 16, v81
	v_and_b32_e32 v74, 0xffff0000, v81
	v_lshlrev_b32_e32 v75, 16, v82
	v_and_b32_e32 v76, 0xffff0000, v82
	s_waitcnt vmcnt(15)
	v_mul_f32_e32 v80, v85, v79
	v_fmac_f32_e32 v80, v84, v71
	v_fmac_f32_e32 v80, v86, v73
	v_fmac_f32_e32 v80, v87, v74
	s_waitcnt vmcnt(14)
	v_fmac_f32_e32 v80, v88, v75
	v_lshlrev_b32_e32 v77, 16, v83
	v_fmac_f32_e32 v80, v89, v76
	v_and_b32_e32 v78, 0xffff0000, v83
	v_fmac_f32_e32 v80, v90, v77
	v_fmac_f32_e32 v80, v91, v78
	s_nop 1
	v_mov_b32_dpp v81, v80 quad_perm:[1,0,3,2] row_mask:0xf bank_mask:0xf
	s_waitcnt lgkmcnt(0)
	v_add_f32_e32 v80, v80, v81
	s_nop 0
	s_nop 1
	v_mov_b32_dpp v81, v80 quad_perm:[2,3,0,1] row_mask:0xf bank_mask:0xf
	s_waitcnt lgkmcnt(0)
	v_add_f32_e32 v80, v80, v81
	s_nop 0
	s_nop 1
	v_mov_b32_dpp v81, v80 row_shl:4 row_mask:0xf bank_mask:0x5
	v_mov_b32_dpp v81, v80 row_shr:4 row_mask:0xf bank_mask:0xa
	s_waitcnt lgkmcnt(0)
	v_add_f32_e32 v81, v80, v81
	s_nop 0
	s_nop 1
	v_mov_b32_dpp v82, v81 row_ror:8 row_mask:0xf bank_mask:0xf
	v_lshl_add_u32 v80, v70, 2, 16
	s_and_saveexec_b64 s[10:11], vcc
	s_cbranch_execz .LBB0_466
	s_waitcnt lgkmcnt(0)
	v_add_f32_e32 v81, v81, v82
	v_mul_f32_e32 v81, 0x3db504f3, v81
	ds_write_b32 v80, v81
.LBB0_466:
	s_or_b64 exec, exec, s[10:11]
	s_waitcnt lgkmcnt(0)
	v_add_u32_e32 v82, 4, v70
	v_ashrrev_i32_e32 v83, 31, v82
	v_lshlrev_b64 v[82:83], 11, v[82:83]
	v_lshl_add_u64 v[86:87], v[68:69], 0, v[82:83]
	s_nop 0
	s_waitcnt vmcnt(12)
	v_mul_f32_e32 v83, v165, v79
	v_fmac_f32_e32 v83, v164, v71
	v_fmac_f32_e32 v83, v166, v73
	v_fmac_f32_e32 v83, v167, v74
	v_fmac_f32_e32 v83, v168, v75
	v_fmac_f32_e32 v83, v169, v76
	v_fmac_f32_e32 v83, v170, v77
	v_fmac_f32_e32 v83, v171, v78
	s_nop 1
	v_mov_b32_dpp v81, v83 quad_perm:[1,0,3,2] row_mask:0xf bank_mask:0xf
	s_waitcnt lgkmcnt(0)
	v_add_f32_e32 v81, v83, v81
	s_nop 1
	v_mov_b32_dpp v82, v81 quad_perm:[2,3,0,1] row_mask:0xf bank_mask:0xf
	s_waitcnt lgkmcnt(0)
	v_add_f32_e32 v81, v81, v82
	s_nop 1
	v_mov_b32_dpp v82, v81 row_shl:4 row_mask:0xf bank_mask:0x5
	v_mov_b32_dpp v82, v81 row_shr:4 row_mask:0xf bank_mask:0xa
	v_mbcnt_lo_u32_b32 v83, -1, 0
	v_mbcnt_hi_u32_b32 v83, -1, v83
	s_waitcnt lgkmcnt(0)
	v_add_f32_e32 v81, v81, v82
	v_lshlrev_b32_e32 v83, 2, v83
	v_xor_b32_e32 v82, 32, v83
	s_nop 1
	v_mov_b32_dpp v82, v81 row_ror:8 row_mask:0xf bank_mask:0xf
	s_and_saveexec_b64 s[10:11], vcc
	s_cbranch_execz .LBB0_468
	s_waitcnt lgkmcnt(0)
	v_add_f32_e32 v81, v81, v82
	v_mul_f32_e32 v81, 0x3db504f3, v81
	ds_write_b32 v80, v81 offset:16
.LBB0_468:
	s_or_b64 exec, exec, s[10:11]
	s_waitcnt lgkmcnt(0)
	v_add_u32_e32 v82, 8, v70
	v_ashrrev_i32_e32 v83, 31, v82
	v_lshlrev_b64 v[82:83], 11, v[82:83]
	v_lshl_add_u64 v[86:87], v[68:69], 0, v[82:83]
	s_nop 0
	s_waitcnt vmcnt(10)
	v_mul_f32_e32 v83, v173, v79
	v_fmac_f32_e32 v83, v172, v71
	v_fmac_f32_e32 v83, v174, v73
	v_fmac_f32_e32 v83, v175, v74
	v_fmac_f32_e32 v83, v176, v75
	v_fmac_f32_e32 v83, v177, v76
	v_fmac_f32_e32 v83, v178, v77
	v_fmac_f32_e32 v83, v179, v78
	s_nop 1
	v_mov_b32_dpp v81, v83 quad_perm:[1,0,3,2] row_mask:0xf bank_mask:0xf
	s_waitcnt lgkmcnt(0)
	v_add_f32_e32 v81, v83, v81
	s_nop 1
	v_mov_b32_dpp v82, v81 quad_perm:[2,3,0,1] row_mask:0xf bank_mask:0xf
	s_waitcnt lgkmcnt(0)
	v_add_f32_e32 v81, v81, v82
	s_nop 1
	v_mov_b32_dpp v82, v81 row_shl:4 row_mask:0xf bank_mask:0x5
	v_mov_b32_dpp v82, v81 row_shr:4 row_mask:0xf bank_mask:0xa
	v_mbcnt_lo_u32_b32 v83, -1, 0
	v_mbcnt_hi_u32_b32 v83, -1, v83
	s_waitcnt lgkmcnt(0)
	v_add_f32_e32 v81, v81, v82
	v_lshlrev_b32_e32 v83, 2, v83
	v_xor_b32_e32 v82, 32, v83
	s_nop 1
	v_mov_b32_dpp v82, v81 row_ror:8 row_mask:0xf bank_mask:0xf
	s_and_saveexec_b64 s[10:11], vcc
	s_cbranch_execz .LBB0_470
	s_waitcnt lgkmcnt(0)
	v_add_f32_e32 v81, v81, v82
	v_mul_f32_e32 v81, 0x3db504f3, v81
	ds_write_b32 v80, v81 offset:32
.LBB0_470:
	s_or_b64 exec, exec, s[10:11]
	s_waitcnt lgkmcnt(0)
	v_add_u32_e32 v82, 12, v70
	v_ashrrev_i32_e32 v83, 31, v82
	v_lshlrev_b64 v[82:83], 11, v[82:83]
	v_lshl_add_u64 v[86:87], v[68:69], 0, v[82:83]
	s_nop 0
	s_waitcnt vmcnt(8)
	v_mul_f32_e32 v83, v181, v79
	v_fmac_f32_e32 v83, v180, v71
	v_fmac_f32_e32 v83, v182, v73
	v_fmac_f32_e32 v83, v183, v74
	v_fmac_f32_e32 v83, v184, v75
	v_fmac_f32_e32 v83, v185, v76
	v_fmac_f32_e32 v83, v186, v77
	v_fmac_f32_e32 v83, v187, v78
	s_nop 1
	v_mov_b32_dpp v81, v83 quad_perm:[1,0,3,2] row_mask:0xf bank_mask:0xf
	s_waitcnt lgkmcnt(0)
	v_add_f32_e32 v81, v83, v81
	s_nop 1
	v_mov_b32_dpp v82, v81 quad_perm:[2,3,0,1] row_mask:0xf bank_mask:0xf
	s_waitcnt lgkmcnt(0)
	v_add_f32_e32 v81, v81, v82
	s_nop 1
	v_mov_b32_dpp v82, v81 row_shl:4 row_mask:0xf bank_mask:0x5
	v_mov_b32_dpp v82, v81 row_shr:4 row_mask:0xf bank_mask:0xa
	v_mbcnt_lo_u32_b32 v83, -1, 0
	v_mbcnt_hi_u32_b32 v83, -1, v83
	s_waitcnt lgkmcnt(0)
	v_add_f32_e32 v81, v81, v82
	v_lshlrev_b32_e32 v83, 2, v83
	v_xor_b32_e32 v82, 32, v83
	s_nop 1
	v_mov_b32_dpp v82, v81 row_ror:8 row_mask:0xf bank_mask:0xf
	s_and_saveexec_b64 s[10:11], vcc
	s_cbranch_execz .LBB0_472
	s_waitcnt lgkmcnt(0)
	v_add_f32_e32 v81, v81, v82
	v_mul_f32_e32 v81, 0x3db504f3, v81
	ds_write_b32 v80, v81 offset:48
; __device__ __forceinline__ float shfl_xor_f(float v, int mask) { const int l = lane_fresh(); return __int_as_float(__builtin_amdgcn_ds_bpermute((l ^ mask) << 2, __float_as_int(v))); }
; __device__ __forceinline__ void attn_sample_item(const Params& p, int item, const int wv) {
;     ...
;     for (int it = 0; it < 8; ++it) {
;       const int mm = wid * 32 + it * 4 + ksub;
;       f32x4 k0 = *(const f32x4*)(Kc + (size_t)mm * 512 + dch * 8), k1 = *(const f32x4*)(Kc + (size_t)mm * 512 + dch * 8 + 4);
;       float d = q[0] * k0[0] + q[1] * k0[1] + q[2] * k0[2] + q[3] * k0[3] + q[4] * k1[0] + q[5] * k1[1] + q[6] * k1[2] + q[7] * k1[3];
;       d += shfl_xor_f(d, 1); d += shfl_xor_f(d, 2); d += shfl_xor_f(d, 4); d += shfl_xor_f(d, 8);
;       if (dch == 0) sc_l[mm] = d * 0.08838834764831845f;
;     }
.LBB0_472:
	s_or_b64 exec, exec, s[10:11]
	s_waitcnt lgkmcnt(0)
	v_add_u32_e32 v82, 16, v70
	v_ashrrev_i32_e32 v83, 31, v82
	v_lshlrev_b64 v[82:83], 11, v[82:83]
	v_lshl_add_u64 v[86:87], v[68:69], 0, v[82:83]
	s_nop 0
	s_waitcnt vmcnt(6)
	v_mul_f32_e32 v83, v189, v79
	v_fmac_f32_e32 v83, v188, v71
	v_fmac_f32_e32 v83, v190, v73
	v_fmac_f32_e32 v83, v191, v74
	v_fmac_f32_e32 v83, v192, v75
	v_fmac_f32_e32 v83, v193, v76
	v_fmac_f32_e32 v83, v194, v77
	v_fmac_f32_e32 v83, v195, v78
	s_nop 1
	v_mov_b32_dpp v81, v83 quad_perm:[1,0,3,2] row_mask:0xf bank_mask:0xf
	s_waitcnt lgkmcnt(0)
	v_add_f32_e32 v81, v83, v81
	s_nop 1
	v_mov_b32_dpp v82, v81 quad_perm:[2,3,0,1] row_mask:0xf bank_mask:0xf
	s_waitcnt lgkmcnt(0)
	v_add_f32_e32 v81, v81, v82
	s_nop 1
	v_mov_b32_dpp v82, v81 row_shl:4 row_mask:0xf bank_mask:0x5
	v_mov_b32_dpp v82, v81 row_shr:4 row_mask:0xf bank_mask:0xa
	v_mbcnt_lo_u32_b32 v83, -1, 0
	v_mbcnt_hi_u32_b32 v83, -1, v83
	s_waitcnt lgkmcnt(0)
	v_add_f32_e32 v81, v81, v82
	v_lshlrev_b32_e32 v83, 2, v83
	v_xor_b32_e32 v82, 32, v83
	s_nop 1
	v_mov_b32_dpp v82, v81 row_ror:8 row_mask:0xf bank_mask:0xf
	s_and_saveexec_b64 s[10:11], vcc
	s_cbranch_execz .LBB0_474
	s_waitcnt lgkmcnt(0)
	v_add_f32_e32 v81, v81, v82
	v_mul_f32_e32 v81, 0x3db504f3, v81
	ds_write_b32 v80, v81 offset:64
.LBB0_474:
	s_or_b64 exec, exec, s[10:11]
	s_waitcnt lgkmcnt(0)
	v_add_u32_e32 v82, 20, v70
	v_ashrrev_i32_e32 v83, 31, v82
	v_lshlrev_b64 v[82:83], 11, v[82:83]
	v_lshl_add_u64 v[86:87], v[68:69], 0, v[82:83]
	s_nop 0
	s_waitcnt vmcnt(4)
	v_mul_f32_e32 v83, v197, v79
	v_fmac_f32_e32 v83, v196, v71
	v_fmac_f32_e32 v83, v198, v73
	v_fmac_f32_e32 v83, v199, v74
	v_fmac_f32_e32 v83, v200, v75
	v_fmac_f32_e32 v83, v201, v76
	v_fmac_f32_e32 v83, v202, v77
	v_fmac_f32_e32 v83, v203, v78
	s_nop 1
	v_mov_b32_dpp v81, v83 quad_perm:[1,0,3,2] row_mask:0xf bank_mask:0xf
	s_waitcnt lgkmcnt(0)
	v_add_f32_e32 v81, v83, v81
	s_nop 1
	v_mov_b32_dpp v82, v81 quad_perm:[2,3,0,1] row_mask:0xf bank_mask:0xf
	s_waitcnt lgkmcnt(0)
	v_add_f32_e32 v81, v81, v82
	s_nop 1
	v_mov_b32_dpp v82, v81 row_shl:4 row_mask:0xf bank_mask:0x5
	v_mov_b32_dpp v82, v81 row_shr:4 row_mask:0xf bank_mask:0xa
	v_mbcnt_lo_u32_b32 v83, -1, 0
	v_mbcnt_hi_u32_b32 v83, -1, v83
	s_waitcnt lgkmcnt(0)
	v_add_f32_e32 v81, v81, v82
	v_lshlrev_b32_e32 v83, 2, v83
	v_xor_b32_e32 v82, 32, v83
	s_nop 1
	v_mov_b32_dpp v82, v81 row_ror:8 row_mask:0xf bank_mask:0xf
	s_and_saveexec_b64 s[10:11], vcc
	s_cbranch_execz .LBB0_476
	s_waitcnt lgkmcnt(0)
	v_add_f32_e32 v81, v81, v82
	v_mul_f32_e32 v81, 0x3db504f3, v81
	ds_write_b32 v80, v81 offset:80
.LBB0_476:
	s_or_b64 exec, exec, s[10:11]
	s_waitcnt lgkmcnt(0)
	v_add_u32_e32 v82, 24, v70
	v_ashrrev_i32_e32 v83, 31, v82
	v_lshlrev_b64 v[82:83], 11, v[82:83]
	v_lshl_add_u64 v[86:87], v[68:69], 0, v[82:83]
	s_nop 0
	s_waitcnt vmcnt(2)
	v_mul_f32_e32 v83, v205, v79
	v_fmac_f32_e32 v83, v204, v71
	v_fmac_f32_e32 v83, v206, v73
	v_fmac_f32_e32 v83, v207, v74
	v_fmac_f32_e32 v83, v208, v75
	v_fmac_f32_e32 v83, v209, v76
	v_fmac_f32_e32 v83, v210, v77
	v_fmac_f32_e32 v83, v211, v78
	s_nop 1
	v_mov_b32_dpp v81, v83 quad_perm:[1,0,3,2] row_mask:0xf bank_mask:0xf
	s_waitcnt lgkmcnt(0)
	v_add_f32_e32 v81, v83, v81
	s_nop 1
	v_mov_b32_dpp v82, v81 quad_perm:[2,3,0,1] row_mask:0xf bank_mask:0xf
	s_waitcnt lgkmcnt(0)
	v_add_f32_e32 v81, v81, v82
	s_nop 1
	v_mov_b32_dpp v82, v81 row_shl:4 row_mask:0xf bank_mask:0x5
	v_mov_b32_dpp v82, v81 row_shr:4 row_mask:0xf bank_mask:0xa
	v_mbcnt_lo_u32_b32 v83, -1, 0
	v_mbcnt_hi_u32_b32 v83, -1, v83
	s_waitcnt lgkmcnt(0)
	v_add_f32_e32 v81, v81, v82
	v_lshlrev_b32_e32 v83, 2, v83
	v_xor_b32_e32 v82, 32, v83
	s_nop 1
	v_mov_b32_dpp v82, v81 row_ror:8 row_mask:0xf bank_mask:0xf
	s_and_saveexec_b64 s[10:11], vcc
	s_cbranch_execz .LBB0_478
	s_waitcnt lgkmcnt(0)
	v_add_f32_e32 v81, v81, v82
	v_mul_f32_e32 v81, 0x3db504f3, v81
	ds_write_b32 v80, v81 offset:96
.LBB0_478:
	s_or_b64 exec, exec, s[10:11]
	s_waitcnt lgkmcnt(0)
	v_add_u32_e32 v82, 28, v70
	v_ashrrev_i32_e32 v83, 31, v82
	v_lshlrev_b64 v[82:83], 11, v[82:83]
	v_lshl_add_u64 v[68:69], v[68:69], 0, v[82:83]
	v_mbcnt_lo_u32_b32 v68, -1, 0
	v_mbcnt_hi_u32_b32 v68, -1, v68
	v_mbcnt_lo_u32_b32 v70, -1, 0
	v_mbcnt_hi_u32_b32 v70, -1, v70
	s_waitcnt vmcnt(0)
	v_mul_f32_e32 v69, v213, v79
	v_fmac_f32_e32 v69, v212, v71
	v_fmac_f32_e32 v69, v214, v73
	v_fmac_f32_e32 v69, v215, v74
	v_fmac_f32_e32 v69, v216, v75
	v_fmac_f32_e32 v69, v217, v76
	v_lshlrev_b32_e32 v68, 2, v68
	v_fmac_f32_e32 v69, v218, v77
	v_xor_b32_e32 v68, 4, v68
	v_fmac_f32_e32 v69, v219, v78
	s_nop 1
	v_mov_b32_dpp v68, v69 quad_perm:[1,0,3,2] row_mask:0xf bank_mask:0xf
	v_lshlrev_b32_e32 v70, 2, v70
	v_xor_b32_e32 v70, 8, v70
	s_waitcnt lgkmcnt(0)
	v_add_f32_e32 v68, v69, v68
	s_nop 1
	v_mov_b32_dpp v69, v68 quad_perm:[2,3,0,1] row_mask:0xf bank_mask:0xf
	s_waitcnt lgkmcnt(0)
	v_add_f32_e32 v68, v68, v69
	s_nop 1
	v_mov_b32_dpp v69, v68 row_shl:4 row_mask:0xf bank_mask:0x5
	v_mov_b32_dpp v69, v68 row_shr:4 row_mask:0xf bank_mask:0xa
	v_mbcnt_lo_u32_b32 v70, -1, 0
	v_mbcnt_hi_u32_b32 v70, -1, v70
	s_waitcnt lgkmcnt(0)
	v_add_f32_e32 v68, v68, v69
	v_lshlrev_b32_e32 v70, 2, v70
	v_xor_b32_e32 v69, 32, v70
	s_nop 1
	v_mov_b32_dpp v69, v68 row_ror:8 row_mask:0xf bank_mask:0xf
	s_and_saveexec_b64 s[10:11], vcc
	s_cbranch_execz .LBB0_480
	s_waitcnt lgkmcnt(0)
	v_add_f32_e32 v68, v68, v69
	v_mul_f32_e32 v68, 0x3db504f3, v68
	ds_write_b32 v80, v68 offset:112
; __device__ __forceinline__ void attn_sample_item(const Params& p, int item, const int wv) {
;     ...
;   float pv[4];
;   {
;     float mx = -1e30f;
; #pragma unroll
;     for (int i = 0; i < 4; ++i) { pv[i] = sc_l[lane + 64 * i]; mx = fmaxf(mx, pv[i]); }
;     mx = wave_max(mx);
;     float sum = 0.f;
; #pragma unroll
;     for (int i = 0; i < 4; ++i) { pv[i] = __expf(pv[i] - mx); sum += pv[i]; }
;     sum = wave_sum(sum);
;     const float inv = 1.f / sum;
; #pragma unroll
;     for (int i = 0; i < 4; ++i) pv[i] *= inv;
;   }
;   __syncthreads();
;   if (wid == 0) {
; #pragma unroll
;     for (int i = 0; i < 4; ++i) sc_l[lane + 64 * i] = pv[i];
;   }
.LBB0_480:
	s_or_b64 exec, exec, s[10:11]
	v_lshl_add_u32 v68, v72, 2, 16
	s_waitcnt lgkmcnt(0)
	s_barrier
	ds_read2st64_b32 v[70:71], v68 offset1:1
	ds_read2st64_b32 v[72:73], v68 offset0:2 offset1:3
	v_mbcnt_lo_u32_b32 v74, -1, 0
	v_mbcnt_hi_u32_b32 v74, -1, v74
	v_mbcnt_lo_u32_b32 v75, -1, 0
	v_mbcnt_hi_u32_b32 v75, -1, v75
	v_readlane_b32 s10, v251, 58
	s_waitcnt lgkmcnt(1)
	v_max3_f32 v69, v70, s17, v71
	v_lshlrev_b32_e32 v74, 2, v74
	s_waitcnt lgkmcnt(0)
	v_max3_f32 v69, v69, v72, v73
	v_xor_b32_e32 v74, 0x80, v74
	ds_bpermute_b32 v74, v74, v69
	v_readlane_b32 s11, v251, 59
	s_and_b64 vcc, exec, s[10:11]
	s_waitcnt lgkmcnt(0)
	v_max_f32_e32 v74, v74, v74
	v_max_f32_e32 v69, v69, v74
	v_lshlrev_b32_e32 v74, 2, v75
	v_xor_b32_e32 v74, 64, v74
	ds_bpermute_b32 v74, v74, v69
	v_mbcnt_lo_u32_b32 v75, -1, 0
	v_mbcnt_hi_u32_b32 v75, -1, v75
	s_waitcnt lgkmcnt(0)
	v_max_f32_e32 v74, v74, v74
	v_lshlrev_b32_e32 v75, 2, v75
	v_max_f32_e32 v69, v69, v74
	v_xor_b32_e32 v74, 32, v75
	s_nop 1
	v_mov_b32_dpp v74, v69 row_ror:8 row_mask:0xf bank_mask:0xf
	s_waitcnt lgkmcnt(0)
	v_max_f32_e32 v74, v74, v74
	v_max_f32_e32 v69, v69, v74
	s_nop 1
	v_mov_b32_dpp v74, v69 row_shl:4 row_mask:0xf bank_mask:0x5
	v_mov_b32_dpp v74, v69 row_shr:4 row_mask:0xf bank_mask:0xa
	s_waitcnt lgkmcnt(0)
	v_max_f32_e32 v74, v74, v74
	v_max_f32_e32 v69, v69, v74
	s_nop 1
	v_mov_b32_dpp v74, v69 quad_perm:[2,3,0,1] row_mask:0xf bank_mask:0xf
	s_waitcnt lgkmcnt(0)
	v_max_f32_e32 v74, v74, v74
	v_max_f32_e32 v69, v69, v74
	s_nop 1
	v_mov_b32_dpp v74, v69 quad_perm:[1,0,3,2] row_mask:0xf bank_mask:0xf
	s_waitcnt lgkmcnt(0)
	v_max_f32_e32 v74, v74, v74
	v_max_f32_e32 v69, v69, v74
	v_sub_f32_e32 v70, v70, v69
	v_sub_f32_e32 v71, v71, v69
	v_sub_f32_e32 v72, v72, v69
	v_sub_f32_e32 v69, v73, v69
	v_mul_f32_e32 v70, 0x3fb8aa3b, v70
	v_mul_f32_e32 v71, 0x3fb8aa3b, v71
	v_mul_f32_e32 v73, 0x3fb8aa3b, v69
	v_exp_f32_e32 v69, v70
	v_mul_f32_e32 v72, 0x3fb8aa3b, v72
	v_exp_f32_e32 v70, v71
	v_exp_f32_e32 v71, v72
	v_exp_f32_e32 v72, v73
	v_add_f32_e32 v73, 0, v69
	v_add_f32_e32 v73, v70, v73
	v_mbcnt_lo_u32_b32 v74, -1, 0
	v_mbcnt_hi_u32_b32 v74, -1, v74
	v_add_f32_e32 v73, v71, v73
	v_lshlrev_b32_e32 v74, 2, v74
	v_add_f32_e32 v73, v72, v73
	v_xor_b32_e32 v74, 0x80, v74
	ds_bpermute_b32 v74, v74, v73
	v_mbcnt_lo_u32_b32 v75, -1, 0
	v_mbcnt_hi_u32_b32 v75, -1, v75
	s_waitcnt lgkmcnt(0)
	v_add_f32_e32 v73, v73, v74
	v_lshlrev_b32_e32 v74, 2, v75
	v_xor_b32_e32 v74, 64, v74
	ds_bpermute_b32 v74, v74, v73
	v_mbcnt_lo_u32_b32 v75, -1, 0
	v_mbcnt_hi_u32_b32 v75, -1, v75
	s_waitcnt lgkmcnt(0)
	v_add_f32_e32 v73, v73, v74
	v_lshlrev_b32_e32 v75, 2, v75
	v_xor_b32_e32 v74, 32, v75
	s_nop 1
	v_mov_b32_dpp v74, v73 row_ror:8 row_mask:0xf bank_mask:0xf
	s_waitcnt lgkmcnt(0)
	v_add_f32_e32 v73, v73, v74
	s_nop 1
	v_mov_b32_dpp v74, v73 row_shl:4 row_mask:0xf bank_mask:0x5
	v_mov_b32_dpp v74, v73 row_shr:4 row_mask:0xf bank_mask:0xa
	s_waitcnt lgkmcnt(0)
	v_add_f32_e32 v73, v73, v74
	s_nop 1
	v_mov_b32_dpp v74, v73 quad_perm:[2,3,0,1] row_mask:0xf bank_mask:0xf
	v_mbcnt_lo_u32_b32 v75, -1, 0
	v_mbcnt_hi_u32_b32 v75, -1, v75
	s_waitcnt lgkmcnt(0)
	v_lshlrev_b32_e32 v75, 2, v75
	s_barrier
	v_add_f32_e32 v73, v73, v74
	v_xor_b32_e32 v74, 4, v75
	s_nop 1
	v_mov_b32_dpp v74, v73 quad_perm:[1,0,3,2] row_mask:0xf bank_mask:0xf
	s_waitcnt lgkmcnt(0)
	s_cbranch_vccnz .LBB0_482
	v_add_f32_e32 v73, v73, v74
	v_div_scale_f32 v74, s[10:11], v73, v73, 1.0
	v_rcp_f32_e32 v75, v74
	v_div_scale_f32 v76, vcc, 1.0, v73, 1.0
	v_fma_f32 v77, -v74, v75, 1.0
	v_fmac_f32_e32 v75, v77, v75
	v_mul_f32_e32 v77, v76, v75
	v_fma_f32 v78, -v74, v77, v76
	v_fmac_f32_e32 v77, v78, v75
	v_fma_f32 v74, -v74, v77, v76
	v_div_fmas_f32 v74, v74, v75, v77
	v_div_fixup_f32 v73, v74, v73, 1.0
	v_mul_f32_e32 v70, v70, v73
	v_mul_f32_e32 v69, v69, v73
	v_mul_f32_e32 v72, v72, v73
	v_mul_f32_e32 v71, v71, v73
	ds_write2st64_b32 v68, v69, v70 offset1:1
	ds_write2st64_b32 v68, v71, v72 offset0:2 offset1:3

; __device__ __forceinline__ float bflo(unsigned w) { return __uint_as_float(w << 16); }
; __device__ __forceinline__ float bfhi(unsigned w) { return __uint_as_float(w & 0xffff0000u); }
; __device__ __forceinline__ void attn_sample_item(const Params& p, int item, const int wv) {
;     ...
;   const float* Kc = p.in[3] + ((size_t)b * 256 * 4 + h) * 128;
;   const float* Vc = p.in[4] + ((size_t)b * 256 * 4 + h) * 128;
;   const int vdch = tid & 31, vmg = tid >> 5;
;   f32x4 vreg[16];
; #pragma unroll
;   for (int i = 0; i < 16; ++i) vreg[i] = *(const f32x4*)(Vc + (size_t)(vmg * 16 + i) * 512 + vdch * 4);
;   __syncthreads();
;   {
;     const int dch = lane & 15, ksub = lane >> 4;
;     u32x4 qw = *(const u32x4*)(Q + (size_t)tok * 512 + h * 128 + dch * 8);
;     float q[8] = {bflo(qw.x), bfhi(qw.x), bflo(qw.y), bfhi(qw.y), bflo(qw.z), bfhi(qw.z), bflo(qw.w), bfhi(qw.w)};
; #pragma unroll
;     for (int it = 0; it < 8; ++it) {
;       const int mm = wid * 32 + it * 4 + ksub;
;       f32x4 k0 = *(const f32x4*)(Kc + (size_t)mm * 512 + dch * 8), k1 = *(const f32x4*)(Kc + (size_t)mm * 512 + dch * 8 + 4);
;       float d = q[0] * k0[0] + q[1] * k0[1] + q[2] * k0[2] + q[3] * k0[3] + q[4] * k1[0] + q[5] * k1[1] + q[6] * k1[2] + q[7] * k1[3];
.LBB0_490:
	s_lshr_b32 s0, s18, 2
	s_and_b32 s19, s14, 0x180
	v_readlane_b32 s64, v251, 6
	s_lshl_b32 s20, s19, 2
	s_lshl_b64 s[8:9], s[0:1], 19
	v_readlane_b32 s72, v251, 14
	v_readlane_b32 s73, v251, 15
	s_or_b32 s8, s8, s20
	s_mov_b64 s[44:45], s[72:73]
	v_mbcnt_lo_u32_b32 v72, -1, 0
	v_mbcnt_hi_u32_b32 v72, -1, v72
	v_readlane_b32 s70, v251, 12
	v_add_u32_e32 v66, s82, v72
	v_readlane_b32 s71, v251, 13
	s_add_u32 s20, s44, s8
	s_mov_b64 s[42:43], s[70:71]
	s_addc_u32 s21, s45, s9
	v_and_b32_e32 v0, 31, v72
	v_ashrrev_i32_e32 v67, 5, v66
	s_addk_i32 s0, 0x4000
	v_lshlrev_b32_e32 v56, 4, v67
	v_lshlrev_b32_e32 v64, 4, v0
	s_add_u32 s8, s42, s8
	v_lshl_add_u64 v[58:59], s[20:21], 0, v[64:65]
	v_ashrrev_i32_e32 v57, 31, v56
	s_addc_u32 s9, s43, s9
	s_lshl_b64 s[20:21], s[0:1], 10
	s_waitcnt lgkmcnt(0)
	v_lshlrev_b64 v[0:1], 11, v[56:57]
	v_or_b32_e32 v2, 1, v56
	v_or_b32_e32 v8, 2, v56
	v_or_b32_e32 v10, 3, v56
	v_or_b32_e32 v16, 4, v56
	v_or_b32_e32 v18, 5, v56
	v_or_b32_e32 v24, 6, v56
	v_or_b32_e32 v26, 7, v56
	v_or_b32_e32 v32, 8, v56
	v_or_b32_e32 v34, 9, v56
	v_or_b32_e32 v40, 10, v56
	v_or_b32_e32 v42, 11, v56
	v_or_b32_e32 v48, 12, v56
	v_or_b32_e32 v50, 13, v56
	v_or_b32_e32 v60, 14, v56
	v_or_b32_e32 v56, 15, v56
	s_add_u32 s20, s10, s20
	v_ashrrev_i32_e32 v3, 31, v2
	v_ashrrev_i32_e32 v9, 31, v8
	v_ashrrev_i32_e32 v11, 31, v10
	v_ashrrev_i32_e32 v17, 31, v16
	v_ashrrev_i32_e32 v19, 31, v18
	v_ashrrev_i32_e32 v25, 31, v24
	v_ashrrev_i32_e32 v27, 31, v26
	v_ashrrev_i32_e32 v33, 31, v32
	v_ashrrev_i32_e32 v35, 31, v34
	v_ashrrev_i32_e32 v41, 31, v40
	v_ashrrev_i32_e32 v43, 31, v42
	v_ashrrev_i32_e32 v49, 31, v48
	v_ashrrev_i32_e32 v51, 31, v50
	v_ashrrev_i32_e32 v61, 31, v60
	v_ashrrev_i32_e32 v57, 31, v56
	s_addc_u32 s21, s11, s21
	s_lshl_b32 s19, s19, 1
	v_lshlrev_b64 v[2:3], 11, v[2:3]
	v_lshlrev_b64 v[8:9], 11, v[8:9]
	v_lshlrev_b64 v[10:11], 11, v[10:11]
	v_lshlrev_b64 v[16:17], 11, v[16:17]
	v_lshlrev_b64 v[18:19], 11, v[18:19]
	v_lshlrev_b64 v[24:25], 11, v[24:25]
	v_lshlrev_b64 v[26:27], 11, v[26:27]
	v_lshlrev_b64 v[32:33], 11, v[32:33]
	v_lshlrev_b64 v[34:35], 11, v[34:35]
	v_lshlrev_b64 v[40:41], 11, v[40:41]
	v_lshlrev_b64 v[42:43], 11, v[42:43]
	v_lshlrev_b64 v[48:49], 11, v[48:49]
	v_lshlrev_b64 v[50:51], 11, v[50:51]
	v_lshlrev_b64 v[60:61], 11, v[60:61]
	v_lshlrev_b64 v[56:57], 11, v[56:57]
	v_and_b32_e32 v92, 15, v72
	v_ashrrev_i32_e32 v68, 4, v72
	s_add_u32 s20, s20, s19
	v_lshl_add_u64 v[0:1], v[58:59], 0, v[0:1]
	v_lshl_add_u64 v[2:3], v[58:59], 0, v[2:3]
	v_lshl_add_u64 v[8:9], v[58:59], 0, v[8:9]
	v_lshl_add_u64 v[10:11], v[58:59], 0, v[10:11]
	v_lshl_add_u64 v[16:17], v[58:59], 0, v[16:17]
	v_lshl_add_u64 v[18:19], v[58:59], 0, v[18:19]
	v_lshl_add_u64 v[24:25], v[58:59], 0, v[24:25]
	v_lshl_add_u64 v[26:27], v[58:59], 0, v[26:27]
	v_lshl_add_u64 v[32:33], v[58:59], 0, v[32:33]
	v_lshl_add_u64 v[34:35], v[58:59], 0, v[34:35]
	v_lshl_add_u64 v[40:41], v[58:59], 0, v[40:41]
	v_lshl_add_u64 v[42:43], v[58:59], 0, v[42:43]
	v_lshl_add_u64 v[48:49], v[58:59], 0, v[48:49]
	v_lshl_add_u64 v[50:51], v[58:59], 0, v[50:51]
	v_lshl_add_u64 v[60:61], v[58:59], 0, v[60:61]
	v_lshl_add_u64 v[56:57], v[58:59], 0, v[56:57]
	s_addc_u32 s21, s21, 0
	v_lshlrev_b32_e32 v69, 4, v92
	v_add_u32_e32 v70, s5, v68
	global_load_dwordx4 v[4:7], v[0:1], off
	s_nop 0
	global_load_dwordx4 v[0:3], v[2:3], off
	s_nop 0
	global_load_dwordx4 v[12:15], v[8:9], off
	s_nop 0
	global_load_dwordx4 v[8:11], v[10:11], off
	s_nop 0
	global_load_dwordx4 v[20:23], v[16:17], off
	s_nop 0
	global_load_dwordx4 v[16:19], v[18:19], off
	s_nop 0
	global_load_dwordx4 v[28:31], v[24:25], off
	s_nop 0
	global_load_dwordx4 v[24:27], v[26:27], off
	s_nop 0
	global_load_dwordx4 v[36:39], v[32:33], off
	s_nop 0
	global_load_dwordx4 v[32:35], v[34:35], off
	s_nop 0
	global_load_dwordx4 v[44:47], v[40:41], off
	s_nop 0
	global_load_dwordx4 v[40:43], v[42:43], off
	s_nop 0
	global_load_dwordx4 v[52:55], v[48:49], off
	s_nop 0
	global_load_dwordx4 v[48:51], v[50:51], off
	s_nop 0
	global_load_dwordx4 v[60:63], v[60:61], off
	s_nop 0
	global_load_dwordx4 v[56:59], v[56:57], off
	s_barrier
	global_load_dwordx4 v[80:83], v69, s[20:21]
	v_lshlrev_b32_e32 v68, 5, v92
	v_mov_b32_e32 v69, v65
	v_ashrrev_i32_e32 v71, 31, v70
	v_lshl_add_u64 v[68:69], s[8:9], 0, v[68:69]
	v_lshlrev_b64 v[74:75], 11, v[70:71]
	v_lshl_add_u64 v[74:75], v[68:69], 0, v[74:75]
	global_load_dwordx4 v[84:87], v[74:75], off
	global_load_dwordx4 v[88:91], v[74:75], off offset:16
	v_mov_b32_e32 v221, 0
	v_mov_b32_e32 v220, 0x2000
	v_lshl_add_u64 v[222:223], v[220:221], 0, v[74:75]
	global_load_dwordx4 v[164:167], v[222:223], off
	global_load_dwordx4 v[168:171], v[222:223], off offset:16
	v_mov_b32_e32 v220, 0x4000
	v_lshl_add_u64 v[222:223], v[220:221], 0, v[74:75]
	global_load_dwordx4 v[172:175], v[222:223], off
	global_load_dwordx4 v[176:179], v[222:223], off offset:16
	v_mov_b32_e32 v220, 0x6000
	v_lshl_add_u64 v[222:223], v[220:221], 0, v[74:75]
	global_load_dwordx4 v[180:183], v[222:223], off
	global_load_dwordx4 v[184:187], v[222:223], off offset:16
	v_mov_b32_e32 v220, 0x8000
	v_lshl_add_u64 v[222:223], v[220:221], 0, v[74:75]
	global_load_dwordx4 v[188:191], v[222:223], off
	global_load_dwordx4 v[192:195], v[222:223], off offset:16
	v_mov_b32_e32 v220, 0xa000
	v_lshl_add_u64 v[222:223], v[220:221], 0, v[74:75]
	global_load_dwordx4 v[196:199], v[222:223], off
	global_load_dwordx4 v[200:203], v[222:223], off offset:16
	v_mov_b32_e32 v220, 0xc000
	v_lshl_add_u64 v[222:223], v[220:221], 0, v[74:75]
	global_load_dwordx4 v[204:207], v[222:223], off
	global_load_dwordx4 v[208:211], v[222:223], off offset:16
	v_mov_b32_e32 v220, 0xe000
	v_lshl_add_u64 v[222:223], v[220:221], 0, v[74:75]
	global_load_dwordx4 v[212:215], v[222:223], off
	global_load_dwordx4 v[216:219], v[222:223], off offset:16
	v_cmp_eq_u32_e32 vcc, 0, v92
	v_readlane_b32 s65, v251, 7
	v_readlane_b32 s66, v251, 8
	v_readlane_b32 s67, v251, 9
	v_readlane_b32 s68, v251, 10
	v_readlane_b32 s69, v251, 11
	v_readlane_b32 s74, v251, 16
	v_readlane_b32 s75, v251, 17
	v_readlane_b32 s76, v251, 18
	v_readlane_b32 s77, v251, 19
	v_readlane_b32 s78, v251, 20
	v_readlane_b32 s79, v251, 21
	s_waitcnt vmcnt(16)
; __device__ __forceinline__ float shfl_xor_f(float v, int mask) { const int l = lane_fresh(); return __int_as_float(__builtin_amdgcn_ds_bpermute((l ^ mask) << 2, __float_as_int(v))); }
; __device__ __forceinline__ void attn_sample_item(const Params& p, int item, const int wv) {
;     ...
;     for (int it = 0; it < 8; ++it) {
;       const int mm = wid * 32 + it * 4 + ksub;
;       f32x4 k0 = *(const f32x4*)(Kc + (size_t)mm * 512 + dch * 8), k1 = *(const f32x4*)(Kc + (size_t)mm * 512 + dch * 8 + 4);
;       float d = q[0] * k0[0] + q[1] * k0[1] + q[2] * k0[2] + q[3] * k0[3] + q[4] * k1[0] + q[5] * k1[1] + q[6] * k1[2] + q[7] * k1[3];
;       d += shfl_xor_f(d, 1); d += shfl_xor_f(d, 2); d += shfl_xor_f(d, 4); d += shfl_xor_f(d, 8);
;       if (dch == 0) sc_l[mm] = d * 0.08838834764831845f;
;     }
	v_and_b32_e32 v79, 0xffff0000, v80
	v_lshlrev_b32_e32 v71, 16, v80
	v_lshlrev_b32_e32 v73, 16, v81
	v_and_b32_e32 v74, 0xffff0000, v81
	v_lshlrev_b32_e32 v75, 16, v82
	v_and_b32_e32 v76, 0xffff0000, v82
	s_waitcnt vmcnt(15)
	v_mul_f32_e32 v80, v85, v79
	v_fmac_f32_e32 v80, v84, v71
	v_fmac_f32_e32 v80, v86, v73
	v_fmac_f32_e32 v80, v87, v74
	s_waitcnt vmcnt(14)
	v_fmac_f32_e32 v80, v88, v75
	v_lshlrev_b32_e32 v77, 16, v83
	v_fmac_f32_e32 v80, v89, v76
	v_and_b32_e32 v78, 0xffff0000, v83
	v_fmac_f32_e32 v80, v90, v77
	v_fmac_f32_e32 v80, v91, v78
	s_nop 1
	v_mov_b32_dpp v81, v80 quad_perm:[1,0,3,2] row_mask:0xf bank_mask:0xf
	s_waitcnt lgkmcnt(0)
	v_add_f32_e32 v80, v80, v81
	s_nop 0
	s_nop 1
	v_mov_b32_dpp v81, v80 quad_perm:[2,3,0,1] row_mask:0xf bank_mask:0xf
	s_waitcnt lgkmcnt(0)
	v_add_f32_e32 v80, v80, v81
	s_nop 0
	s_nop 1
	v_mov_b32_dpp v81, v80 row_shl:4 row_mask:0xf bank_mask:0x5
	v_mov_b32_dpp v81, v80 row_shr:4 row_mask:0xf bank_mask:0xa
	s_waitcnt lgkmcnt(0)
	v_add_f32_e32 v81, v80, v81
	s_nop 0
	s_nop 1
	v_mov_b32_dpp v82, v81 row_ror:8 row_mask:0xf bank_mask:0xf
	v_lshl_add_u32 v80, v70, 2, 16
	s_and_saveexec_b64 s[8:9], vcc
	s_cbranch_execz .LBB0_492
	s_waitcnt lgkmcnt(0)
	v_add_f32_e32 v81, v81, v82
	v_mul_f32_e32 v81, 0x3db504f3, v81
	ds_write_b32 v80, v81
.LBB0_492:
	s_or_b64 exec, exec, s[8:9]
	s_waitcnt lgkmcnt(0)
	v_add_u32_e32 v82, 4, v70
	v_ashrrev_i32_e32 v83, 31, v82
	v_lshlrev_b64 v[82:83], 11, v[82:83]
	v_lshl_add_u64 v[86:87], v[68:69], 0, v[82:83]
	s_nop 0
	s_waitcnt vmcnt(12)
	v_mul_f32_e32 v83, v165, v79
	v_fmac_f32_e32 v83, v164, v71
	v_fmac_f32_e32 v83, v166, v73
	v_fmac_f32_e32 v83, v167, v74
	v_fmac_f32_e32 v83, v168, v75
	v_fmac_f32_e32 v83, v169, v76
	v_fmac_f32_e32 v83, v170, v77
	v_fmac_f32_e32 v83, v171, v78
	s_nop 1
	v_mov_b32_dpp v81, v83 quad_perm:[1,0,3,2] row_mask:0xf bank_mask:0xf
	s_waitcnt lgkmcnt(0)
	v_add_f32_e32 v81, v83, v81
	s_nop 1
	v_mov_b32_dpp v82, v81 quad_perm:[2,3,0,1] row_mask:0xf bank_mask:0xf
	s_waitcnt lgkmcnt(0)
	v_add_f32_e32 v81, v81, v82
	s_nop 1
	v_mov_b32_dpp v82, v81 row_shl:4 row_mask:0xf bank_mask:0x5
	v_mov_b32_dpp v82, v81 row_shr:4 row_mask:0xf bank_mask:0xa
	v_mbcnt_lo_u32_b32 v83, -1, 0
	v_mbcnt_hi_u32_b32 v83, -1, v83
	s_waitcnt lgkmcnt(0)
	v_add_f32_e32 v81, v81, v82
	v_lshlrev_b32_e32 v83, 2, v83
	v_xor_b32_e32 v82, 32, v83
	s_nop 1
	v_mov_b32_dpp v82, v81 row_ror:8 row_mask:0xf bank_mask:0xf
	s_and_saveexec_b64 s[8:9], vcc
	s_cbranch_execz .LBB0_494
	s_waitcnt lgkmcnt(0)
	v_add_f32_e32 v81, v81, v82
	v_mul_f32_e32 v81, 0x3db504f3, v81
	ds_write_b32 v80, v81 offset:16
.LBB0_494:
	s_or_b64 exec, exec, s[8:9]
	s_waitcnt lgkmcnt(0)
	v_add_u32_e32 v82, 8, v70
	v_ashrrev_i32_e32 v83, 31, v82
	v_lshlrev_b64 v[82:83], 11, v[82:83]
	v_lshl_add_u64 v[86:87], v[68:69], 0, v[82:83]
	s_nop 0
	s_waitcnt vmcnt(10)
	v_mul_f32_e32 v83, v173, v79
	v_fmac_f32_e32 v83, v172, v71
	v_fmac_f32_e32 v83, v174, v73
	v_fmac_f32_e32 v83, v175, v74
	v_fmac_f32_e32 v83, v176, v75
	v_fmac_f32_e32 v83, v177, v76
	v_fmac_f32_e32 v83, v178, v77
	v_fmac_f32_e32 v83, v179, v78
	s_nop 1
	v_mov_b32_dpp v81, v83 quad_perm:[1,0,3,2] row_mask:0xf bank_mask:0xf
	s_waitcnt lgkmcnt(0)
	v_add_f32_e32 v81, v83, v81
	s_nop 1
	v_mov_b32_dpp v82, v81 quad_perm:[2,3,0,1] row_mask:0xf bank_mask:0xf
	s_waitcnt lgkmcnt(0)
	v_add_f32_e32 v81, v81, v82
	s_nop 1
	v_mov_b32_dpp v82, v81 row_shl:4 row_mask:0xf bank_mask:0x5
	v_mov_b32_dpp v82, v81 row_shr:4 row_mask:0xf bank_mask:0xa
	v_mbcnt_lo_u32_b32 v83, -1, 0
	v_mbcnt_hi_u32_b32 v83, -1, v83
	s_waitcnt lgkmcnt(0)
	v_add_f32_e32 v81, v81, v82
	v_lshlrev_b32_e32 v83, 2, v83
	v_xor_b32_e32 v82, 32, v83
	s_nop 1
	v_mov_b32_dpp v82, v81 row_ror:8 row_mask:0xf bank_mask:0xf
	s_and_saveexec_b64 s[8:9], vcc
	s_cbranch_execz .LBB0_496
	s_waitcnt lgkmcnt(0)
	v_add_f32_e32 v81, v81, v82
	v_mul_f32_e32 v81, 0x3db504f3, v81
	ds_write_b32 v80, v81 offset:32
.LBB0_496:
	s_or_b64 exec, exec, s[8:9]
	s_waitcnt lgkmcnt(0)
	v_add_u32_e32 v82, 12, v70
	v_ashrrev_i32_e32 v83, 31, v82
	v_lshlrev_b64 v[82:83], 11, v[82:83]
	v_lshl_add_u64 v[86:87], v[68:69], 0, v[82:83]
	s_nop 0
	s_waitcnt vmcnt(8)
	v_mul_f32_e32 v83, v181, v79
	v_fmac_f32_e32 v83, v180, v71
	v_fmac_f32_e32 v83, v182, v73
	v_fmac_f32_e32 v83, v183, v74
	v_fmac_f32_e32 v83, v184, v75
	v_fmac_f32_e32 v83, v185, v76
	v_fmac_f32_e32 v83, v186, v77
	v_fmac_f32_e32 v83, v187, v78
	s_nop 1
	v_mov_b32_dpp v81, v83 quad_perm:[1,0,3,2] row_mask:0xf bank_mask:0xf
	s_waitcnt lgkmcnt(0)
	v_add_f32_e32 v81, v83, v81
	s_nop 1
	v_mov_b32_dpp v82, v81 quad_perm:[2,3,0,1] row_mask:0xf bank_mask:0xf
	s_waitcnt lgkmcnt(0)
	v_add_f32_e32 v81, v81, v82
	s_nop 1
	v_mov_b32_dpp v82, v81 row_shl:4 row_mask:0xf bank_mask:0x5
	v_mov_b32_dpp v82, v81 row_shr:4 row_mask:0xf bank_mask:0xa
	v_mbcnt_lo_u32_b32 v83, -1, 0
	v_mbcnt_hi_u32_b32 v83, -1, v83
	s_waitcnt lgkmcnt(0)
	v_add_f32_e32 v81, v81, v82
	v_lshlrev_b32_e32 v83, 2, v83
	v_xor_b32_e32 v82, 32, v83
	s_nop 1
	v_mov_b32_dpp v82, v81 row_ror:8 row_mask:0xf bank_mask:0xf
	s_and_saveexec_b64 s[8:9], vcc
	s_cbranch_execz .LBB0_498
	s_waitcnt lgkmcnt(0)
	v_add_f32_e32 v81, v81, v82
	v_mul_f32_e32 v81, 0x3db504f3, v81
	ds_write_b32 v80, v81 offset:48
; __device__ __forceinline__ float shfl_xor_f(float v, int mask) { const int l = lane_fresh(); return __int_as_float(__builtin_amdgcn_ds_bpermute((l ^ mask) << 2, __float_as_int(v))); }
; __device__ __forceinline__ void attn_sample_item(const Params& p, int item, const int wv) {
;     ...
;     for (int it = 0; it < 8; ++it) {
;       const int mm = wid * 32 + it * 4 + ksub;
;       f32x4 k0 = *(const f32x4*)(Kc + (size_t)mm * 512 + dch * 8), k1 = *(const f32x4*)(Kc + (size_t)mm * 512 + dch * 8 + 4);
;       float d = q[0] * k0[0] + q[1] * k0[1] + q[2] * k0[2] + q[3] * k0[3] + q[4] * k1[0] + q[5] * k1[1] + q[6] * k1[2] + q[7] * k1[3];
;       d += shfl_xor_f(d, 1); d += shfl_xor_f(d, 2); d += shfl_xor_f(d, 4); d += shfl_xor_f(d, 8);
;       if (dch == 0) sc_l[mm] = d * 0.08838834764831845f;
;     }
.LBB0_498:
	s_or_b64 exec, exec, s[8:9]
	s_waitcnt lgkmcnt(0)
	v_add_u32_e32 v82, 16, v70
	v_ashrrev_i32_e32 v83, 31, v82
	v_lshlrev_b64 v[82:83], 11, v[82:83]
	v_lshl_add_u64 v[86:87], v[68:69], 0, v[82:83]
	s_nop 0
	s_waitcnt vmcnt(6)
	v_mul_f32_e32 v83, v189, v79
	v_fmac_f32_e32 v83, v188, v71
	v_fmac_f32_e32 v83, v190, v73
	v_fmac_f32_e32 v83, v191, v74
	v_fmac_f32_e32 v83, v192, v75
	v_fmac_f32_e32 v83, v193, v76
	v_fmac_f32_e32 v83, v194, v77
	v_fmac_f32_e32 v83, v195, v78
	s_nop 1
	v_mov_b32_dpp v81, v83 quad_perm:[1,0,3,2] row_mask:0xf bank_mask:0xf
	s_waitcnt lgkmcnt(0)
	v_add_f32_e32 v81, v83, v81
	s_nop 1
	v_mov_b32_dpp v82, v81 quad_perm:[2,3,0,1] row_mask:0xf bank_mask:0xf
	s_waitcnt lgkmcnt(0)
	v_add_f32_e32 v81, v81, v82
	s_nop 1
	v_mov_b32_dpp v82, v81 row_shl:4 row_mask:0xf bank_mask:0x5
	v_mov_b32_dpp v82, v81 row_shr:4 row_mask:0xf bank_mask:0xa
	v_mbcnt_lo_u32_b32 v83, -1, 0
	v_mbcnt_hi_u32_b32 v83, -1, v83
	s_waitcnt lgkmcnt(0)
	v_add_f32_e32 v81, v81, v82
	v_lshlrev_b32_e32 v83, 2, v83
	v_xor_b32_e32 v82, 32, v83
	s_nop 1
	v_mov_b32_dpp v82, v81 row_ror:8 row_mask:0xf bank_mask:0xf
	s_and_saveexec_b64 s[8:9], vcc
	s_cbranch_execz .LBB0_500
	s_waitcnt lgkmcnt(0)
	v_add_f32_e32 v81, v81, v82
	v_mul_f32_e32 v81, 0x3db504f3, v81
	ds_write_b32 v80, v81 offset:64
.LBB0_500:
	s_or_b64 exec, exec, s[8:9]
	s_waitcnt lgkmcnt(0)
	v_add_u32_e32 v82, 20, v70
	v_ashrrev_i32_e32 v83, 31, v82
	v_lshlrev_b64 v[82:83], 11, v[82:83]
	v_lshl_add_u64 v[86:87], v[68:69], 0, v[82:83]
	s_nop 0
	s_waitcnt vmcnt(4)
	v_mul_f32_e32 v83, v197, v79
	v_fmac_f32_e32 v83, v196, v71
	v_fmac_f32_e32 v83, v198, v73
	v_fmac_f32_e32 v83, v199, v74
	v_fmac_f32_e32 v83, v200, v75
	v_fmac_f32_e32 v83, v201, v76
	v_fmac_f32_e32 v83, v202, v77
	v_fmac_f32_e32 v83, v203, v78
	s_nop 1
	v_mov_b32_dpp v81, v83 quad_perm:[1,0,3,2] row_mask:0xf bank_mask:0xf
	s_waitcnt lgkmcnt(0)
	v_add_f32_e32 v81, v83, v81
	s_nop 1
	v_mov_b32_dpp v82, v81 quad_perm:[2,3,0,1] row_mask:0xf bank_mask:0xf
	s_waitcnt lgkmcnt(0)
	v_add_f32_e32 v81, v81, v82
	s_nop 1
	v_mov_b32_dpp v82, v81 row_shl:4 row_mask:0xf bank_mask:0x5
	v_mov_b32_dpp v82, v81 row_shr:4 row_mask:0xf bank_mask:0xa
	v_mbcnt_lo_u32_b32 v83, -1, 0
	v_mbcnt_hi_u32_b32 v83, -1, v83
	s_waitcnt lgkmcnt(0)
	v_add_f32_e32 v81, v81, v82
	v_lshlrev_b32_e32 v83, 2, v83
	v_xor_b32_e32 v82, 32, v83
	s_nop 1
	v_mov_b32_dpp v82, v81 row_ror:8 row_mask:0xf bank_mask:0xf
	s_and_saveexec_b64 s[8:9], vcc
	s_cbranch_execz .LBB0_502
	s_waitcnt lgkmcnt(0)
	v_add_f32_e32 v81, v81, v82
	v_mul_f32_e32 v81, 0x3db504f3, v81
	ds_write_b32 v80, v81 offset:80
.LBB0_502:
	s_or_b64 exec, exec, s[8:9]
	s_waitcnt lgkmcnt(0)
	v_add_u32_e32 v82, 24, v70
	v_ashrrev_i32_e32 v83, 31, v82
	v_lshlrev_b64 v[82:83], 11, v[82:83]
	v_lshl_add_u64 v[86:87], v[68:69], 0, v[82:83]
	s_nop 0
	s_waitcnt vmcnt(2)
	v_mul_f32_e32 v83, v205, v79
	v_fmac_f32_e32 v83, v204, v71
	v_fmac_f32_e32 v83, v206, v73
	v_fmac_f32_e32 v83, v207, v74
	v_fmac_f32_e32 v83, v208, v75
	v_fmac_f32_e32 v83, v209, v76
	v_fmac_f32_e32 v83, v210, v77
	v_fmac_f32_e32 v83, v211, v78
	s_nop 1
	v_mov_b32_dpp v81, v83 quad_perm:[1,0,3,2] row_mask:0xf bank_mask:0xf
	s_waitcnt lgkmcnt(0)
	v_add_f32_e32 v81, v83, v81
	s_nop 1
	v_mov_b32_dpp v82, v81 quad_perm:[2,3,0,1] row_mask:0xf bank_mask:0xf
	s_waitcnt lgkmcnt(0)
	v_add_f32_e32 v81, v81, v82
	s_nop 1
	v_mov_b32_dpp v82, v81 row_shl:4 row_mask:0xf bank_mask:0x5
	v_mov_b32_dpp v82, v81 row_shr:4 row_mask:0xf bank_mask:0xa
	v_mbcnt_lo_u32_b32 v83, -1, 0
	v_mbcnt_hi_u32_b32 v83, -1, v83
	s_waitcnt lgkmcnt(0)
	v_add_f32_e32 v81, v81, v82
	v_lshlrev_b32_e32 v83, 2, v83
	v_xor_b32_e32 v82, 32, v83
	s_nop 1
	v_mov_b32_dpp v82, v81 row_ror:8 row_mask:0xf bank_mask:0xf
	s_and_saveexec_b64 s[8:9], vcc
	s_cbranch_execz .LBB0_504
	s_waitcnt lgkmcnt(0)
	v_add_f32_e32 v81, v81, v82
	v_mul_f32_e32 v81, 0x3db504f3, v81
	ds_write_b32 v80, v81 offset:96
.LBB0_504:
	s_or_b64 exec, exec, s[8:9]
	s_waitcnt lgkmcnt(0)
	v_add_u32_e32 v82, 28, v70
	v_ashrrev_i32_e32 v83, 31, v82
	v_lshlrev_b64 v[82:83], 11, v[82:83]
	v_lshl_add_u64 v[68:69], v[68:69], 0, v[82:83]
	v_mbcnt_lo_u32_b32 v68, -1, 0
	v_mbcnt_hi_u32_b32 v68, -1, v68
	v_mbcnt_lo_u32_b32 v70, -1, 0
	v_mbcnt_hi_u32_b32 v70, -1, v70
	s_waitcnt vmcnt(0)
	v_mul_f32_e32 v69, v213, v79
	v_fmac_f32_e32 v69, v212, v71
	v_fmac_f32_e32 v69, v214, v73
	v_fmac_f32_e32 v69, v215, v74
	v_fmac_f32_e32 v69, v216, v75
	v_fmac_f32_e32 v69, v217, v76
	v_lshlrev_b32_e32 v68, 2, v68
	v_fmac_f32_e32 v69, v218, v77
	v_xor_b32_e32 v68, 4, v68
	v_fmac_f32_e32 v69, v219, v78
	s_nop 1
	v_mov_b32_dpp v68, v69 quad_perm:[1,0,3,2] row_mask:0xf bank_mask:0xf
	v_lshlrev_b32_e32 v70, 2, v70
	v_xor_b32_e32 v70, 8, v70
	s_waitcnt lgkmcnt(0)
	v_add_f32_e32 v68, v69, v68
	s_nop 1
	v_mov_b32_dpp v69, v68 quad_perm:[2,3,0,1] row_mask:0xf bank_mask:0xf
	s_waitcnt lgkmcnt(0)
	v_add_f32_e32 v68, v68, v69
	s_nop 1
	v_mov_b32_dpp v69, v68 row_shl:4 row_mask:0xf bank_mask:0x5
	v_mov_b32_dpp v69, v68 row_shr:4 row_mask:0xf bank_mask:0xa
	v_mbcnt_lo_u32_b32 v70, -1, 0
	v_mbcnt_hi_u32_b32 v70, -1, v70
	s_waitcnt lgkmcnt(0)
	v_add_f32_e32 v68, v68, v69
	v_lshlrev_b32_e32 v70, 2, v70
	v_xor_b32_e32 v69, 32, v70
	s_nop 1
	v_mov_b32_dpp v69, v68 row_ror:8 row_mask:0xf bank_mask:0xf
	s_and_saveexec_b64 s[8:9], vcc
	s_cbranch_execz .LBB0_506
	s_waitcnt lgkmcnt(0)
	v_add_f32_e32 v68, v68, v69
	v_mul_f32_e32 v68, 0x3db504f3, v68
	ds_write_b32 v80, v68 offset:112
; __device__ __forceinline__ void attn_sample_item(const Params& p, int item, const int wv) {
;     ...
;   float pv[4];
;   {
;     float mx = -1e30f;
; #pragma unroll
;     for (int i = 0; i < 4; ++i) { pv[i] = sc_l[lane + 64 * i]; mx = fmaxf(mx, pv[i]); }
;     mx = wave_max(mx);
;     float sum = 0.f;
; #pragma unroll
;     for (int i = 0; i < 4; ++i) { pv[i] = __expf(pv[i] - mx); sum += pv[i]; }
;     sum = wave_sum(sum);
;     const float inv = 1.f / sum;
; #pragma unroll
;     for (int i = 0; i < 4; ++i) pv[i] *= inv;
;   }
;   __syncthreads();
;   if (wid == 0) {
; #pragma unroll
;     for (int i = 0; i < 4; ++i) sc_l[lane + 64 * i] = pv[i];
;   }
.LBB0_506:
	s_or_b64 exec, exec, s[8:9]
	v_lshl_add_u32 v68, v72, 2, 16
	s_waitcnt lgkmcnt(0)
	s_barrier
	ds_read2st64_b32 v[70:71], v68 offset1:1
	ds_read2st64_b32 v[72:73], v68 offset0:2 offset1:3
	v_mbcnt_lo_u32_b32 v74, -1, 0
	v_mbcnt_hi_u32_b32 v74, -1, v74
	v_mbcnt_lo_u32_b32 v75, -1, 0
	v_mbcnt_hi_u32_b32 v75, -1, v75
	v_readlane_b32 s8, v251, 58
	s_waitcnt lgkmcnt(1)
	v_max3_f32 v69, v70, s16, v71
	v_lshlrev_b32_e32 v74, 2, v74
	s_waitcnt lgkmcnt(0)
	v_max3_f32 v69, v69, v72, v73
	v_xor_b32_e32 v74, 0x80, v74
	ds_bpermute_b32 v74, v74, v69
	v_readlane_b32 s9, v251, 59
	s_and_b64 vcc, exec, s[8:9]
	s_waitcnt lgkmcnt(0)
	v_max_f32_e32 v74, v74, v74
	v_max_f32_e32 v69, v69, v74
	v_lshlrev_b32_e32 v74, 2, v75
	v_xor_b32_e32 v74, 64, v74
	ds_bpermute_b32 v74, v74, v69
	v_mbcnt_lo_u32_b32 v75, -1, 0
	v_mbcnt_hi_u32_b32 v75, -1, v75
	s_waitcnt lgkmcnt(0)
	v_max_f32_e32 v74, v74, v74
	v_lshlrev_b32_e32 v75, 2, v75
	v_max_f32_e32 v69, v69, v74
	v_xor_b32_e32 v74, 32, v75
	s_nop 1
	v_mov_b32_dpp v74, v69 row_ror:8 row_mask:0xf bank_mask:0xf
	s_waitcnt lgkmcnt(0)
	v_max_f32_e32 v74, v74, v74
	v_max_f32_e32 v69, v69, v74
	s_nop 1
	v_mov_b32_dpp v74, v69 row_shl:4 row_mask:0xf bank_mask:0x5
	v_mov_b32_dpp v74, v69 row_shr:4 row_mask:0xf bank_mask:0xa
	s_waitcnt lgkmcnt(0)
	v_max_f32_e32 v74, v74, v74
	v_max_f32_e32 v69, v69, v74
	s_nop 1
	v_mov_b32_dpp v74, v69 quad_perm:[2,3,0,1] row_mask:0xf bank_mask:0xf
	s_waitcnt lgkmcnt(0)
	v_max_f32_e32 v74, v74, v74
	v_max_f32_e32 v69, v69, v74
	s_nop 1
	v_mov_b32_dpp v74, v69 quad_perm:[1,0,3,2] row_mask:0xf bank_mask:0xf
	s_waitcnt lgkmcnt(0)
	v_max_f32_e32 v74, v74, v74
	v_max_f32_e32 v69, v69, v74
	v_sub_f32_e32 v70, v70, v69
	v_sub_f32_e32 v71, v71, v69
	v_sub_f32_e32 v72, v72, v69
	v_sub_f32_e32 v69, v73, v69
	v_mul_f32_e32 v70, 0x3fb8aa3b, v70
	v_mul_f32_e32 v71, 0x3fb8aa3b, v71
	v_mul_f32_e32 v73, 0x3fb8aa3b, v69
	v_exp_f32_e32 v69, v70
	v_mul_f32_e32 v72, 0x3fb8aa3b, v72
	v_exp_f32_e32 v70, v71
	v_exp_f32_e32 v71, v72
	v_exp_f32_e32 v72, v73
	v_add_f32_e32 v73, 0, v69
	v_add_f32_e32 v73, v70, v73
	v_mbcnt_lo_u32_b32 v74, -1, 0
	v_mbcnt_hi_u32_b32 v74, -1, v74
	v_add_f32_e32 v73, v71, v73
	v_lshlrev_b32_e32 v74, 2, v74
	v_add_f32_e32 v73, v72, v73
	v_xor_b32_e32 v74, 0x80, v74
	ds_bpermute_b32 v74, v74, v73
	v_mbcnt_lo_u32_b32 v75, -1, 0
	v_mbcnt_hi_u32_b32 v75, -1, v75
	s_waitcnt lgkmcnt(0)
	v_add_f32_e32 v73, v73, v74
	v_lshlrev_b32_e32 v74, 2, v75
	v_xor_b32_e32 v74, 64, v74
	ds_bpermute_b32 v74, v74, v73
	v_mbcnt_lo_u32_b32 v75, -1, 0
	v_mbcnt_hi_u32_b32 v75, -1, v75
	s_waitcnt lgkmcnt(0)
	v_add_f32_e32 v73, v73, v74
	v_lshlrev_b32_e32 v75, 2, v75
	v_xor_b32_e32 v74, 32, v75
	s_nop 1
	v_mov_b32_dpp v74, v73 row_ror:8 row_mask:0xf bank_mask:0xf
	s_waitcnt lgkmcnt(0)
	v_add_f32_e32 v73, v73, v74
	s_nop 1
	v_mov_b32_dpp v74, v73 row_shl:4 row_mask:0xf bank_mask:0x5
	v_mov_b32_dpp v74, v73 row_shr:4 row_mask:0xf bank_mask:0xa
	s_waitcnt lgkmcnt(0)
	v_add_f32_e32 v73, v73, v74
	s_nop 1
	v_mov_b32_dpp v74, v73 quad_perm:[2,3,0,1] row_mask:0xf bank_mask:0xf
	v_mbcnt_lo_u32_b32 v75, -1, 0
	v_mbcnt_hi_u32_b32 v75, -1, v75
	s_waitcnt lgkmcnt(0)
	v_lshlrev_b32_e32 v75, 2, v75
	s_barrier
	v_add_f32_e32 v73, v73, v74
	v_xor_b32_e32 v74, 4, v75
	s_nop 1
	v_mov_b32_dpp v74, v73 quad_perm:[1,0,3,2] row_mask:0xf bank_mask:0xf
	s_waitcnt lgkmcnt(0)
	s_cbranch_vccnz .LBB0_508
	v_add_f32_e32 v73, v73, v74
	v_div_scale_f32 v74, s[8:9], v73, v73, 1.0
	v_rcp_f32_e32 v75, v74
	v_div_scale_f32 v76, vcc, 1.0, v73, 1.0
	v_fma_f32 v77, -v74, v75, 1.0
	v_fmac_f32_e32 v75, v77, v75
	v_mul_f32_e32 v77, v76, v75
	v_fma_f32 v78, -v74, v77, v76
	v_fmac_f32_e32 v77, v78, v75
	v_fma_f32 v74, -v74, v77, v76
	v_div_fmas_f32 v74, v74, v75, v77
	v_div_fixup_f32 v73, v74, v73, 1.0
	v_mul_f32_e32 v70, v70, v73
	v_mul_f32_e32 v69, v69, v73
	v_mul_f32_e32 v72, v72, v73
	v_mul_f32_e32 v71, v71, v73
	ds_write2st64_b32 v68, v69, v70 offset1:1
	ds_write2st64_b32 v68, v71, v72 offset0:2 offset1:3

; __device__ __forceinline__ float shfl_xor_f(float v, int mask) { const int l = lane_fresh(); return __int_as_float(__builtin_amdgcn_ds_bpermute((l ^ mask) << 2, __float_as_int(v))); }
; __device__ __forceinline__ void attn_sample_item(const Params& p, int item, const int wv) {
;     ...
;     for (int it = 0; it < 8; ++it) {
;       const int mm = wid * 32 + it * 4 + ksub;
;       f32x4 k0 = *(const f32x4*)(Kc + (size_t)mm * 512 + dch * 8), k1 = *(const f32x4*)(Kc + (size_t)mm * 512 + dch * 8 + 4);
;       float d = q[0] * k0[0] + q[1] * k0[1] + q[2] * k0[2] + q[3] * k0[3] + q[4] * k1[0] + q[5] * k1[1] + q[6] * k1[2] + q[7] * k1[3];
;       d += shfl_xor_f(d, 1); d += shfl_xor_f(d, 2); d += shfl_xor_f(d, 4); d += shfl_xor_f(d, 8);
;       if (dch == 0) sc_l[mm] = d * 0.08838834764831845f;
;     }
.LBB0_514:
	s_or_b64 exec, exec, s[8:9]
	v_add_u32_e32 v80, 4, v70
	s_waitcnt lgkmcnt(0)
	v_ashrrev_i32_e32 v81, 31, v80
	v_lshlrev_b64 v[80:81], 11, v[80:81]
	v_lshl_add_u64 v[84:85], v[68:69], 0, v[80:81]
	s_nop 0
	v_mbcnt_lo_u32_b32 v88, -1, 0
	v_mbcnt_hi_u32_b32 v88, -1, v88
	s_waitcnt vmcnt(12)
	v_mul_f32_e32 v81, v165, v78
	v_fmac_f32_e32 v81, v164, v67
	v_fmac_f32_e32 v81, v166, v71
	v_fmac_f32_e32 v81, v167, v73
	v_fmac_f32_e32 v81, v168, v74
	v_fmac_f32_e32 v81, v169, v75
	v_lshlrev_b32_e32 v88, 2, v88
	v_fmac_f32_e32 v81, v170, v76
	v_xor_b32_e32 v88, 4, v88
	v_fmac_f32_e32 v81, v171, v77
	s_nop 1
	v_mov_b32_dpp v80, v81 quad_perm:[1,0,3,2] row_mask:0xf bank_mask:0xf
	s_waitcnt lgkmcnt(0)
	v_add_f32_e32 v80, v81, v80
	s_nop 1
	v_mov_b32_dpp v81, v80 quad_perm:[2,3,0,1] row_mask:0xf bank_mask:0xf
	s_waitcnt lgkmcnt(0)
	v_add_f32_e32 v80, v80, v81
	s_nop 1
	v_mov_b32_dpp v81, v80 row_shl:4 row_mask:0xf bank_mask:0x5
	v_mov_b32_dpp v81, v80 row_shr:4 row_mask:0xf bank_mask:0xa
	v_mbcnt_lo_u32_b32 v82, -1, 0
	v_mbcnt_hi_u32_b32 v82, -1, v82
	s_waitcnt lgkmcnt(0)
	v_add_f32_e32 v80, v80, v81
	v_lshlrev_b32_e32 v82, 2, v82
	v_xor_b32_e32 v81, 32, v82
	s_nop 1
	v_mov_b32_dpp v81, v80 row_ror:8 row_mask:0xf bank_mask:0xf
	s_and_saveexec_b64 s[8:9], vcc
	s_cbranch_execz .LBB0_516
	s_waitcnt lgkmcnt(0)
	v_add_f32_e32 v80, v80, v81
	v_mul_f32_e32 v80, 0x3db504f3, v80
	ds_write_b32 v79, v80 offset:16
.LBB0_516:
	s_or_b64 exec, exec, s[8:9]
	v_add_u32_e32 v80, 8, v70
	s_waitcnt lgkmcnt(0)
	v_ashrrev_i32_e32 v81, 31, v80
	v_lshlrev_b64 v[80:81], 11, v[80:81]
	v_lshl_add_u64 v[84:85], v[68:69], 0, v[80:81]
	s_nop 0
	v_mbcnt_lo_u32_b32 v88, -1, 0
	v_mbcnt_hi_u32_b32 v88, -1, v88
	s_waitcnt vmcnt(10)
	v_mul_f32_e32 v81, v173, v78
	v_fmac_f32_e32 v81, v172, v67
	v_fmac_f32_e32 v81, v174, v71
	v_fmac_f32_e32 v81, v175, v73
	v_fmac_f32_e32 v81, v176, v74
	v_fmac_f32_e32 v81, v177, v75
	v_lshlrev_b32_e32 v88, 2, v88
	v_fmac_f32_e32 v81, v178, v76
	v_xor_b32_e32 v88, 4, v88
	v_fmac_f32_e32 v81, v179, v77
	s_nop 1
	v_mov_b32_dpp v80, v81 quad_perm:[1,0,3,2] row_mask:0xf bank_mask:0xf
	s_waitcnt lgkmcnt(0)
	v_add_f32_e32 v80, v81, v80
	s_nop 1
	v_mov_b32_dpp v81, v80 quad_perm:[2,3,0,1] row_mask:0xf bank_mask:0xf
	s_waitcnt lgkmcnt(0)
	v_add_f32_e32 v80, v80, v81
	s_nop 1
	v_mov_b32_dpp v81, v80 row_shl:4 row_mask:0xf bank_mask:0x5
	v_mov_b32_dpp v81, v80 row_shr:4 row_mask:0xf bank_mask:0xa
	v_mbcnt_lo_u32_b32 v82, -1, 0
	v_mbcnt_hi_u32_b32 v82, -1, v82
	s_waitcnt lgkmcnt(0)
	v_add_f32_e32 v80, v80, v81
	v_lshlrev_b32_e32 v82, 2, v82
	v_xor_b32_e32 v81, 32, v82
	s_nop 1
	v_mov_b32_dpp v81, v80 row_ror:8 row_mask:0xf bank_mask:0xf
	s_and_saveexec_b64 s[8:9], vcc
	s_cbranch_execz .LBB0_518
	s_waitcnt lgkmcnt(0)
	v_add_f32_e32 v80, v80, v81
	v_mul_f32_e32 v80, 0x3db504f3, v80
	ds_write_b32 v79, v80 offset:32
.LBB0_518:
	s_or_b64 exec, exec, s[8:9]
	v_add_u32_e32 v80, 12, v70
	s_waitcnt lgkmcnt(0)
	v_ashrrev_i32_e32 v81, 31, v80
	v_lshlrev_b64 v[80:81], 11, v[80:81]
	v_lshl_add_u64 v[84:85], v[68:69], 0, v[80:81]
	s_nop 0
	v_mbcnt_lo_u32_b32 v88, -1, 0
	v_mbcnt_hi_u32_b32 v88, -1, v88
	s_waitcnt vmcnt(8)
	v_mul_f32_e32 v81, v181, v78
	v_fmac_f32_e32 v81, v180, v67
	v_fmac_f32_e32 v81, v182, v71
	v_fmac_f32_e32 v81, v183, v73
	v_fmac_f32_e32 v81, v184, v74
	v_fmac_f32_e32 v81, v185, v75
	v_lshlrev_b32_e32 v88, 2, v88
	v_fmac_f32_e32 v81, v186, v76
	v_xor_b32_e32 v88, 4, v88
	v_fmac_f32_e32 v81, v187, v77
	s_nop 1
	v_mov_b32_dpp v80, v81 quad_perm:[1,0,3,2] row_mask:0xf bank_mask:0xf
	s_waitcnt lgkmcnt(0)
	v_add_f32_e32 v80, v81, v80
	s_nop 1
	v_mov_b32_dpp v81, v80 quad_perm:[2,3,0,1] row_mask:0xf bank_mask:0xf
	s_waitcnt lgkmcnt(0)
	v_add_f32_e32 v80, v80, v81
	s_nop 1
	v_mov_b32_dpp v81, v80 row_shl:4 row_mask:0xf bank_mask:0x5
	v_mov_b32_dpp v81, v80 row_shr:4 row_mask:0xf bank_mask:0xa
	v_mbcnt_lo_u32_b32 v82, -1, 0
	v_mbcnt_hi_u32_b32 v82, -1, v82
	s_waitcnt lgkmcnt(0)
	v_add_f32_e32 v80, v80, v81
	v_lshlrev_b32_e32 v82, 2, v82
	v_xor_b32_e32 v81, 32, v82
	s_nop 1
	v_mov_b32_dpp v81, v80 row_ror:8 row_mask:0xf bank_mask:0xf
	s_and_saveexec_b64 s[8:9], vcc
	s_cbranch_execz .LBB0_520
	s_waitcnt lgkmcnt(0)
	v_add_f32_e32 v80, v80, v81
	v_mul_f32_e32 v80, 0x3db504f3, v80
	ds_write_b32 v79, v80 offset:48
.LBB0_520:
	s_or_b64 exec, exec, s[8:9]
	v_add_u32_e32 v80, 16, v70
	s_waitcnt lgkmcnt(0)
	v_ashrrev_i32_e32 v81, 31, v80
	v_lshlrev_b64 v[80:81], 11, v[80:81]
	v_lshl_add_u64 v[84:85], v[68:69], 0, v[80:81]
	s_nop 0
	v_mbcnt_lo_u32_b32 v88, -1, 0
	v_mbcnt_hi_u32_b32 v88, -1, v88
	s_waitcnt vmcnt(6)
	v_mul_f32_e32 v81, v189, v78
	v_fmac_f32_e32 v81, v188, v67
	v_fmac_f32_e32 v81, v190, v71
	v_fmac_f32_e32 v81, v191, v73
	v_fmac_f32_e32 v81, v192, v74
	v_fmac_f32_e32 v81, v193, v75
	v_lshlrev_b32_e32 v88, 2, v88
	v_fmac_f32_e32 v81, v194, v76
	v_xor_b32_e32 v88, 4, v88
	v_fmac_f32_e32 v81, v195, v77
	s_nop 1
	v_mov_b32_dpp v80, v81 quad_perm:[1,0,3,2] row_mask:0xf bank_mask:0xf
	s_waitcnt lgkmcnt(0)
	v_add_f32_e32 v80, v81, v80
	s_nop 1
	v_mov_b32_dpp v81, v80 quad_perm:[2,3,0,1] row_mask:0xf bank_mask:0xf
	s_waitcnt lgkmcnt(0)
	v_add_f32_e32 v80, v80, v81
	s_nop 1
	v_mov_b32_dpp v81, v80 row_shl:4 row_mask:0xf bank_mask:0x5
	v_mov_b32_dpp v81, v80 row_shr:4 row_mask:0xf bank_mask:0xa
	v_mbcnt_lo_u32_b32 v82, -1, 0
	v_mbcnt_hi_u32_b32 v82, -1, v82
	s_waitcnt lgkmcnt(0)
	v_add_f32_e32 v80, v80, v81
	v_lshlrev_b32_e32 v82, 2, v82
	v_xor_b32_e32 v81, 32, v82
	s_nop 1
	v_mov_b32_dpp v81, v80 row_ror:8 row_mask:0xf bank_mask:0xf
	s_and_saveexec_b64 s[8:9], vcc
	s_cbranch_execz .LBB0_522
	s_waitcnt lgkmcnt(0)
	v_add_f32_e32 v80, v80, v81
	v_mul_f32_e32 v80, 0x3db504f3, v80
	ds_write_b32 v79, v80 offset:64
; __device__ __forceinline__ float shfl_xor_f(float v, int mask) { const int l = lane_fresh(); return __int_as_float(__builtin_amdgcn_ds_bpermute((l ^ mask) << 2, __float_as_int(v))); }
; __device__ __forceinline__ void attn_sample_item(const Params& p, int item, const int wv) {
;     ...
;     for (int it = 0; it < 8; ++it) {
;       const int mm = wid * 32 + it * 4 + ksub;
;       f32x4 k0 = *(const f32x4*)(Kc + (size_t)mm * 512 + dch * 8), k1 = *(const f32x4*)(Kc + (size_t)mm * 512 + dch * 8 + 4);
;       float d = q[0] * k0[0] + q[1] * k0[1] + q[2] * k0[2] + q[3] * k0[3] + q[4] * k1[0] + q[5] * k1[1] + q[6] * k1[2] + q[7] * k1[3];
;       d += shfl_xor_f(d, 1); d += shfl_xor_f(d, 2); d += shfl_xor_f(d, 4); d += shfl_xor_f(d, 8);
;       if (dch == 0) sc_l[mm] = d * 0.08838834764831845f;
;     }
.LBB0_522:
	s_or_b64 exec, exec, s[8:9]
	v_add_u32_e32 v80, 20, v70
	s_waitcnt lgkmcnt(0)
	v_ashrrev_i32_e32 v81, 31, v80
	v_lshlrev_b64 v[80:81], 11, v[80:81]
	v_lshl_add_u64 v[84:85], v[68:69], 0, v[80:81]
	s_nop 0
	v_mbcnt_lo_u32_b32 v88, -1, 0
	v_mbcnt_hi_u32_b32 v88, -1, v88
	s_waitcnt vmcnt(4)
	v_mul_f32_e32 v81, v197, v78
	v_fmac_f32_e32 v81, v196, v67
	v_fmac_f32_e32 v81, v198, v71
	v_fmac_f32_e32 v81, v199, v73
	v_fmac_f32_e32 v81, v200, v74
	v_fmac_f32_e32 v81, v201, v75
	v_lshlrev_b32_e32 v88, 2, v88
	v_fmac_f32_e32 v81, v202, v76
	v_xor_b32_e32 v88, 4, v88
	v_fmac_f32_e32 v81, v203, v77
	s_nop 1
	v_mov_b32_dpp v80, v81 quad_perm:[1,0,3,2] row_mask:0xf bank_mask:0xf
	s_waitcnt lgkmcnt(0)
	v_add_f32_e32 v80, v81, v80
	s_nop 1
	v_mov_b32_dpp v81, v80 quad_perm:[2,3,0,1] row_mask:0xf bank_mask:0xf
	s_waitcnt lgkmcnt(0)
	v_add_f32_e32 v80, v80, v81
	s_nop 1
	v_mov_b32_dpp v81, v80 row_shl:4 row_mask:0xf bank_mask:0x5
	v_mov_b32_dpp v81, v80 row_shr:4 row_mask:0xf bank_mask:0xa
	v_mbcnt_lo_u32_b32 v82, -1, 0
	v_mbcnt_hi_u32_b32 v82, -1, v82
	s_waitcnt lgkmcnt(0)
	v_add_f32_e32 v80, v80, v81
	v_lshlrev_b32_e32 v82, 2, v82
	v_xor_b32_e32 v81, 32, v82
	s_nop 1
	v_mov_b32_dpp v81, v80 row_ror:8 row_mask:0xf bank_mask:0xf
	s_and_saveexec_b64 s[8:9], vcc
	s_cbranch_execz .LBB0_524
	s_waitcnt lgkmcnt(0)
	v_add_f32_e32 v80, v80, v81
	v_mul_f32_e32 v80, 0x3db504f3, v80
	ds_write_b32 v79, v80 offset:80
.LBB0_524:
	s_or_b64 exec, exec, s[8:9]
	v_add_u32_e32 v80, 24, v70
	s_waitcnt lgkmcnt(0)
	v_ashrrev_i32_e32 v81, 31, v80
	v_lshlrev_b64 v[80:81], 11, v[80:81]
	v_lshl_add_u64 v[84:85], v[68:69], 0, v[80:81]
	s_nop 0
	v_mbcnt_lo_u32_b32 v88, -1, 0
	v_mbcnt_hi_u32_b32 v88, -1, v88
	s_waitcnt vmcnt(2)
	v_mul_f32_e32 v81, v205, v78
	v_fmac_f32_e32 v81, v204, v67
	v_fmac_f32_e32 v81, v206, v71
	v_fmac_f32_e32 v81, v207, v73
	v_fmac_f32_e32 v81, v208, v74
	v_fmac_f32_e32 v81, v209, v75
	v_lshlrev_b32_e32 v88, 2, v88
	v_fmac_f32_e32 v81, v210, v76
	v_xor_b32_e32 v88, 4, v88
	v_fmac_f32_e32 v81, v211, v77
	s_nop 1
	v_mov_b32_dpp v80, v81 quad_perm:[1,0,3,2] row_mask:0xf bank_mask:0xf
	s_waitcnt lgkmcnt(0)
	v_add_f32_e32 v80, v81, v80
	s_nop 1
	v_mov_b32_dpp v81, v80 quad_perm:[2,3,0,1] row_mask:0xf bank_mask:0xf
	s_waitcnt lgkmcnt(0)
	v_add_f32_e32 v80, v80, v81
	s_nop 1
	v_mov_b32_dpp v81, v80 row_shl:4 row_mask:0xf bank_mask:0x5
	v_mov_b32_dpp v81, v80 row_shr:4 row_mask:0xf bank_mask:0xa
	v_mbcnt_lo_u32_b32 v82, -1, 0
	v_mbcnt_hi_u32_b32 v82, -1, v82
	s_waitcnt lgkmcnt(0)
	v_add_f32_e32 v80, v80, v81
	v_lshlrev_b32_e32 v82, 2, v82
	v_xor_b32_e32 v81, 32, v82
	s_nop 1
	v_mov_b32_dpp v81, v80 row_ror:8 row_mask:0xf bank_mask:0xf
	s_and_saveexec_b64 s[8:9], vcc
	s_cbranch_execz .LBB0_526
	s_waitcnt lgkmcnt(0)
	v_add_f32_e32 v80, v80, v81
	v_mul_f32_e32 v80, 0x3db504f3, v80
	ds_write_b32 v79, v80 offset:96
.LBB0_526:
	s_or_b64 exec, exec, s[8:9]
	v_add_u32_e32 v80, 28, v70
	s_waitcnt lgkmcnt(0)
	v_ashrrev_i32_e32 v81, 31, v80
	v_lshlrev_b64 v[80:81], 11, v[80:81]
	v_lshl_add_u64 v[68:69], v[68:69], 0, v[80:81]
	s_waitcnt vmcnt(0)
	v_mul_f32_e32 v69, v213, v78
	v_fmac_f32_e32 v69, v212, v67
	v_fmac_f32_e32 v69, v214, v71
	v_fmac_f32_e32 v69, v215, v73
	v_fmac_f32_e32 v69, v216, v74
	v_fmac_f32_e32 v69, v217, v75
	v_fmac_f32_e32 v69, v218, v76
	v_fmac_f32_e32 v69, v219, v77
	s_nop 1
	v_mov_b32_dpp v67, v69 quad_perm:[1,0,3,2] row_mask:0xf bank_mask:0xf
	s_waitcnt lgkmcnt(0)
	v_add_f32_e32 v67, v69, v67
	s_nop 1
	v_mov_b32_dpp v68, v67 quad_perm:[2,3,0,1] row_mask:0xf bank_mask:0xf
	s_waitcnt lgkmcnt(0)
	v_add_f32_e32 v67, v67, v68
	s_nop 1
	v_mov_b32_dpp v68, v67 row_shl:4 row_mask:0xf bank_mask:0x5
	v_mov_b32_dpp v68, v67 row_shr:4 row_mask:0xf bank_mask:0xa
	v_mbcnt_lo_u32_b32 v69, -1, 0
	v_mbcnt_hi_u32_b32 v69, -1, v69
	s_waitcnt lgkmcnt(0)
	v_add_f32_e32 v67, v67, v68
	v_lshlrev_b32_e32 v69, 2, v69
	v_xor_b32_e32 v68, 32, v69
	s_nop 1
	v_mov_b32_dpp v68, v67 row_ror:8 row_mask:0xf bank_mask:0xf
	s_and_saveexec_b64 s[8:9], vcc
	s_cbranch_execz .LBB0_528
	s_waitcnt lgkmcnt(0)
	v_add_f32_e32 v67, v67, v68
	v_mul_f32_e32 v67, 0x3db504f3, v67
	ds_write_b32 v79, v67 offset:112
; __device__ __forceinline__ void attn_sample_item(const Params& p, int item, const int wv) {
;     ...
;   __syncthreads();
;   float pv[4];
;   {
;     float mx = -1e30f;
; #pragma unroll
;     for (int i = 0; i < 4; ++i) { pv[i] = sc_l[lane + 64 * i]; mx = fmaxf(mx, pv[i]); }
;     mx = wave_max(mx);
;     float sum = 0.f;
; #pragma unroll
;     for (int i = 0; i < 4; ++i) { pv[i] = __expf(pv[i] - mx); sum += pv[i]; }
;     sum = wave_sum(sum);
;     const float inv = 1.f / sum;
; #pragma unroll
;     for (int i = 0; i < 4; ++i) pv[i] *= inv;
;   }
;   __syncthreads();
;   if (wid == 0) {
; #pragma unroll
;     for (int i = 0; i < 4; ++i) sc_l[lane + 64 * i] = pv[i];
;   }
.LBB0_528:
	s_or_b64 exec, exec, s[8:9]
	v_lshl_add_u32 v67, v72, 2, 16
	s_waitcnt lgkmcnt(0)
	s_barrier
	ds_read2st64_b32 v[68:69], v67 offset1:1
	ds_read2st64_b32 v[70:71], v67 offset0:2 offset1:3
	s_mov_b32 s7, 0xf149f2ca
	v_mbcnt_lo_u32_b32 v73, -1, 0
	v_mbcnt_hi_u32_b32 v73, -1, v73
	v_readlane_b32 s8, v251, 58
	s_waitcnt lgkmcnt(1)
	v_max3_f32 v72, v68, s7, v69
	v_lshlrev_b32_e32 v73, 2, v73
	s_waitcnt lgkmcnt(0)
	v_max3_f32 v72, v72, v70, v71
	v_xor_b32_e32 v73, 0x80, v73
	ds_bpermute_b32 v73, v73, v72
	v_readlane_b32 s9, v251, 59
	s_movk_i32 s7, 0x80
	s_and_b64 vcc, exec, s[8:9]
	s_waitcnt lgkmcnt(0)
	v_max_f32_e32 v73, v73, v73
	v_max_f32_e32 v72, v72, v73
	v_mbcnt_lo_u32_b32 v73, -1, 0
	v_mbcnt_hi_u32_b32 v73, -1, v73
	v_mbcnt_lo_u32_b32 v74, -1, 0
	v_mbcnt_hi_u32_b32 v74, -1, v74
	s_nop 0
	v_lshlrev_b32_e32 v73, 2, v73
	v_xor_b32_e32 v73, 64, v73
	ds_bpermute_b32 v73, v73, v72
	s_waitcnt lgkmcnt(0)
	v_max_f32_e32 v73, v73, v73
	v_max_f32_e32 v72, v72, v73
	v_lshlrev_b32_e32 v73, 2, v74
	v_xor_b32_e32 v73, 32, v73
	s_nop 1
	v_mov_b32_dpp v73, v72 row_ror:8 row_mask:0xf bank_mask:0xf
	v_mbcnt_lo_u32_b32 v74, -1, 0
	v_mbcnt_hi_u32_b32 v74, -1, v74
	s_waitcnt lgkmcnt(0)
	v_max_f32_e32 v73, v73, v73
	v_lshlrev_b32_e32 v74, 2, v74
	v_max_f32_e32 v72, v72, v73
	v_xor_b32_e32 v73, 16, v74
	s_nop 1
	v_mov_b32_dpp v73, v72 row_shl:4 row_mask:0xf bank_mask:0x5
	v_mov_b32_dpp v73, v72 row_shr:4 row_mask:0xf bank_mask:0xa
	s_waitcnt lgkmcnt(0)
	v_max_f32_e32 v73, v73, v73
	v_max_f32_e32 v72, v72, v73
	s_nop 1
	v_mov_b32_dpp v73, v72 quad_perm:[2,3,0,1] row_mask:0xf bank_mask:0xf
	s_waitcnt lgkmcnt(0)
	v_max_f32_e32 v73, v73, v73
	v_max_f32_e32 v72, v72, v73
	s_nop 1
	v_mov_b32_dpp v73, v72 quad_perm:[1,0,3,2] row_mask:0xf bank_mask:0xf
	s_waitcnt lgkmcnt(0)
	v_max_f32_e32 v73, v73, v73
	v_max_f32_e32 v72, v72, v73
	v_sub_f32_e32 v68, v68, v72
	v_sub_f32_e32 v69, v69, v72
	v_mul_f32_e32 v68, 0x3fb8aa3b, v68
	v_sub_f32_e32 v70, v70, v72
	v_mul_f32_e32 v69, 0x3fb8aa3b, v69
	v_exp_f32_e32 v68, v68
	v_mul_f32_e32 v70, 0x3fb8aa3b, v70
	v_exp_f32_e32 v69, v69
	v_sub_f32_e32 v71, v71, v72
	v_exp_f32_e32 v70, v70
	v_mul_f32_e32 v71, 0x3fb8aa3b, v71
	v_exp_f32_e32 v71, v71
	v_add_f32_e32 v72, 0, v68
	v_add_f32_e32 v72, v69, v72
	v_mbcnt_lo_u32_b32 v73, -1, 0
	v_mbcnt_hi_u32_b32 v73, -1, v73
	v_add_f32_e32 v72, v70, v72
	v_lshlrev_b32_e32 v73, 2, v73
	v_add_f32_e32 v72, v71, v72
	v_xor_b32_e32 v73, 0x80, v73
	ds_bpermute_b32 v73, v73, v72
	s_waitcnt lgkmcnt(0)
	v_add_f32_e32 v72, v72, v73
	v_mbcnt_lo_u32_b32 v73, -1, 0
	v_mbcnt_hi_u32_b32 v73, -1, v73
	v_mbcnt_lo_u32_b32 v74, -1, 0
	v_mbcnt_hi_u32_b32 v74, -1, v74
	s_nop 0
	v_lshlrev_b32_e32 v73, 2, v73
	v_xor_b32_e32 v73, 64, v73
	ds_bpermute_b32 v73, v73, v72
	s_waitcnt lgkmcnt(0)
	v_add_f32_e32 v72, v72, v73
	v_lshlrev_b32_e32 v73, 2, v74
	v_xor_b32_e32 v73, 32, v73
	s_nop 1
	v_mov_b32_dpp v73, v72 row_ror:8 row_mask:0xf bank_mask:0xf
	v_mbcnt_lo_u32_b32 v74, -1, 0
	v_mbcnt_hi_u32_b32 v74, -1, v74
	s_waitcnt lgkmcnt(0)
	v_add_f32_e32 v72, v72, v73
	v_lshlrev_b32_e32 v74, 2, v74
	v_xor_b32_e32 v73, 16, v74
	s_nop 1
	v_mov_b32_dpp v73, v72 row_shl:4 row_mask:0xf bank_mask:0x5
	v_mov_b32_dpp v73, v72 row_shr:4 row_mask:0xf bank_mask:0xa
	s_waitcnt lgkmcnt(0)
	v_add_f32_e32 v72, v72, v73
	s_nop 1
	v_mov_b32_dpp v73, v72 quad_perm:[2,3,0,1] row_mask:0xf bank_mask:0xf
	v_mbcnt_lo_u32_b32 v74, -1, 0
	v_mbcnt_hi_u32_b32 v74, -1, v74
	s_waitcnt lgkmcnt(0)
	v_lshlrev_b32_e32 v74, 2, v74
	s_barrier
	v_add_f32_e32 v72, v72, v73
	v_xor_b32_e32 v73, 4, v74
	s_nop 1
	v_mov_b32_dpp v73, v72 quad_perm:[1,0,3,2] row_mask:0xf bank_mask:0xf
	s_waitcnt lgkmcnt(0)
	s_cbranch_vccnz .LBB0_530
	v_add_f32_e32 v72, v72, v73
	v_div_scale_f32 v73, s[8:9], v72, v72, 1.0
	v_rcp_f32_e32 v74, v73
	v_div_scale_f32 v75, vcc, 1.0, v72, 1.0
	v_fma_f32 v76, -v73, v74, 1.0
	v_fmac_f32_e32 v74, v76, v74
	v_mul_f32_e32 v76, v75, v74
	v_fma_f32 v77, -v73, v76, v75
	v_fmac_f32_e32 v76, v77, v74
	v_fma_f32 v73, -v73, v76, v75
	v_div_fmas_f32 v73, v73, v74, v76
	v_div_fixup_f32 v72, v73, v72, 1.0
	v_mul_f32_e32 v69, v69, v72
	v_mul_f32_e32 v68, v68, v72
	v_mul_f32_e32 v71, v71, v72
	v_mul_f32_e32 v70, v70, v72
	ds_write2st64_b32 v67, v68, v69 offset1:1
	ds_write2st64_b32 v67, v70, v71 offset0:2 offset1:3
